# removed compiler-inserted vmcnt(0) before ds_read in 10 GEMM k-loops (prefetch now overlaps compute)
# speedup vs baseline: 1.0681x; 1.0681x over previous
; __device__ __forceinline__ f32x4 mfma16(bf16x8 a, bf16x8 b, f32x4 c) { return __builtin_amdgcn_mfma_f32_16x16x32_bf16(a, b, c, 0, 0, 0); }
; template <class Epi>
; __device__ __forceinline__ void gemm_tile(const bf16_t* __restrict__ A, const bf16_t* __restrict__ Bt, int K, int row0, int col0, const Epi& epi, char* smem,
;                                           bool prefetched, bool nvalid, int nrow0, int ncol0) {
;     ...
;     for (int kt = 0; kt < nk; ++kt) {
;         const int cur = kt & 1;
;         if (kt + 1 < nk) GLDS_STAGE(cur ^ 1, pA, pB, kt + 1);
;         const char* cb = smem + cur * 2 * TILE_B;
; #pragma unroll
;         for (int ks = 0; ks < 2; ++ks) {
;             bf16x8 a[4], b[4];
; #pragma unroll
;             for (int m = 0; m < 4; ++m) a[m] = *(const bf16x8*)(cb + offA[m][ks]);
; #pragma unroll
;             for (int n = 0; n < 4; ++n) b[n] = *(const bf16x8*)(cb + offB[n][ks]);
; #pragma unroll
;             for (int m = 0; m < 4; ++m)
; #pragma unroll
;                 for (int n = 0; n < 4; ++n) acc[m][n] = mfma16(b[n], a[m], acc[m][n]);
;         }
;         asm volatile("s_waitcnt vmcnt(0)" ::: "memory");
;         __syncthreads();
;     }
.LBB0_154:
	s_and_b32 s8, s5, 0x8000
	s_xor_b32 s9, s8, 0x8000
	v_add_u32_e32 v182, s9, v149
	v_add_u32_e32 v183, 0x4000, v182
	v_readfirstlane_b32 s9, v182
	v_lshl_add_u64 v[80:81], v[64:65], 0, s[0:1]
	v_add_u32_e32 v184, 0x1000, v182
	v_readfirstlane_b32 s10, v183
	s_mov_b32 m0, s9
	v_lshl_add_u64 v[82:83], v[72:73], 0, s[0:1]
	v_add_u32_e32 v185, 0x5000, v182
	v_readfirstlane_b32 s11, v184
	global_load_lds_dwordx4 v[80:81], off
	s_mov_b32 m0, s10
	v_lshl_add_u64 v[128:129], v[66:67], 0, s[0:1]
	v_add_u32_e32 v187, 0x2000, v182
	v_readfirstlane_b32 s12, v185
	global_load_lds_dwordx4 v[82:83], off
	s_mov_b32 m0, s11
	v_lshl_add_u64 v[130:131], v[74:75], 0, s[0:1]
	v_add_u32_e32 v188, 0x6000, v182
	v_readfirstlane_b32 s13, v187
	global_load_lds_dwordx4 v[128:129], off
	s_mov_b32 m0, s12
	v_lshl_add_u64 v[174:175], v[68:69], 0, s[0:1]
	v_add_u32_e32 v189, 0x3000, v182
	v_readfirstlane_b32 s14, v188
	global_load_lds_dwordx4 v[130:131], off
	s_mov_b32 m0, s13
	v_lshl_add_u64 v[176:177], v[76:77], 0, s[0:1]
	v_add_u32_e32 v182, 0x7000, v182
	v_readfirstlane_b32 s15, v189
	global_load_lds_dwordx4 v[174:175], off
	s_mov_b32 m0, s14
	v_lshl_add_u64 v[178:179], v[70:71], 0, s[0:1]
	v_readfirstlane_b32 s16, v182
	global_load_lds_dwordx4 v[176:177], off
	s_mov_b32 m0, s15
	v_lshl_add_u64 v[180:181], v[78:79], 0, s[0:1]
	global_load_lds_dwordx4 v[178:179], off
	s_mov_b32 m0, s16
	v_or_b32_e32 v186, s8, v142
	global_load_lds_dwordx4 v[180:181], off
	v_add_u32_e32 v173, s8, v139
	ds_read_b128 v[80:83], v186 offset:16384
	ds_read_b128 v[128:131], v186 offset:16896
	ds_read_b128 v[174:177], v173
	ds_read_b128 v[178:181], v173 offset:2048
	ds_read_b128 v[182:185], v186 offset:20480
	ds_read_b128 v[186:189], v186 offset:20992
	s_waitcnt lgkmcnt(0)
	v_mfma_f32_16x16x32_bf16 v[0:3], v[80:83], v[174:177], v[0:3]
	v_or_b32_e32 v190, s8, v141
	s_add_i32 s5, s5, 0x8000
	s_add_u32 s0, s0, 0x80
	v_mfma_f32_16x16x32_bf16 v[4:7], v[128:131], v[174:177], v[4:7]
	s_addc_u32 s1, s1, 0
	s_cmpk_eq_i32 s0, 0x780
	v_mfma_f32_16x16x32_bf16 v[8:11], v[182:185], v[174:177], v[8:11]
	v_mfma_f32_16x16x32_bf16 v[12:15], v[186:189], v[174:177], v[12:15]
	v_mfma_f32_16x16x32_bf16 v[16:19], v[80:83], v[178:181], v[16:19]
	v_mfma_f32_16x16x32_bf16 v[20:23], v[128:131], v[178:181], v[20:23]
	v_mfma_f32_16x16x32_bf16 v[24:27], v[182:185], v[178:181], v[24:27]
	v_mfma_f32_16x16x32_bf16 v[28:31], v[186:189], v[178:181], v[28:31]
	ds_read_b128 v[174:177], v173 offset:4096
	ds_read_b128 v[178:181], v173 offset:6144
	v_add_u32_e32 v173, s8, v140
	s_waitcnt lgkmcnt(1)
	v_mfma_f32_16x16x32_bf16 v[32:35], v[80:83], v[174:177], v[32:35]
	v_mfma_f32_16x16x32_bf16 v[36:39], v[128:131], v[174:177], v[36:39]
	v_mfma_f32_16x16x32_bf16 v[40:43], v[182:185], v[174:177], v[40:43]
	v_mfma_f32_16x16x32_bf16 v[44:47], v[186:189], v[174:177], v[44:47]
	s_waitcnt lgkmcnt(0)
	v_mfma_f32_16x16x32_bf16 v[48:51], v[80:83], v[178:181], v[48:51]
	v_mfma_f32_16x16x32_bf16 v[52:55], v[128:131], v[178:181], v[52:55]
	ds_read_b128 v[80:83], v190 offset:16384
	ds_read_b128 v[128:131], v190 offset:16896
	v_mfma_f32_16x16x32_bf16 v[56:59], v[182:185], v[178:181], v[56:59]
	v_mfma_f32_16x16x32_bf16 v[60:63], v[186:189], v[178:181], v[60:63]
	ds_read_b128 v[174:177], v173
	ds_read_b128 v[178:181], v173 offset:2048
	ds_read_b128 v[182:185], v190 offset:20480
	ds_read_b128 v[186:189], v190 offset:20992
	s_waitcnt lgkmcnt(3)
	v_mfma_f32_16x16x32_bf16 v[0:3], v[80:83], v[174:177], v[0:3]
	v_mfma_f32_16x16x32_bf16 v[4:7], v[128:131], v[174:177], v[4:7]
	s_waitcnt lgkmcnt(1)
	v_mfma_f32_16x16x32_bf16 v[8:11], v[182:185], v[174:177], v[8:11]
	s_waitcnt lgkmcnt(0)
	v_mfma_f32_16x16x32_bf16 v[12:15], v[186:189], v[174:177], v[12:15]
	v_mfma_f32_16x16x32_bf16 v[16:19], v[80:83], v[178:181], v[16:19]
	v_mfma_f32_16x16x32_bf16 v[20:23], v[128:131], v[178:181], v[20:23]
	v_mfma_f32_16x16x32_bf16 v[24:27], v[182:185], v[178:181], v[24:27]
	v_mfma_f32_16x16x32_bf16 v[28:31], v[186:189], v[178:181], v[28:31]
	ds_read_b128 v[174:177], v173 offset:4096
	ds_read_b128 v[178:181], v173 offset:6144
	s_waitcnt vmcnt(0)
	s_waitcnt lgkmcnt(0)
	v_mfma_f32_16x16x32_bf16 v[32:35], v[80:83], v[174:177], v[32:35]
	s_barrier
	v_mfma_f32_16x16x32_bf16 v[36:39], v[128:131], v[174:177], v[36:39]
	v_mfma_f32_16x16x32_bf16 v[40:43], v[182:185], v[174:177], v[40:43]
	v_mfma_f32_16x16x32_bf16 v[44:47], v[186:189], v[174:177], v[44:47]
	v_mfma_f32_16x16x32_bf16 v[48:51], v[80:83], v[178:181], v[48:51]
	v_mfma_f32_16x16x32_bf16 v[52:55], v[128:131], v[178:181], v[52:55]
	v_mfma_f32_16x16x32_bf16 v[56:59], v[182:185], v[178:181], v[56:59]
	v_mfma_f32_16x16x32_bf16 v[60:63], v[186:189], v[178:181], v[60:63]
	s_cbranch_scc0 .LBB0_154
; __device__ __forceinline__ f32x4 mfma16(bf16x8 a, bf16x8 b, f32x4 c) { return __builtin_amdgcn_mfma_f32_16x16x32_bf16(a, b, c, 0, 0, 0); }
; template <class Epi>
; __device__ __forceinline__ void gemm_tile(const bf16_t* __restrict__ A, const bf16_t* __restrict__ Bt, int K, int row0, int col0, const Epi& epi, char* smem,
;                                           bool prefetched, bool nvalid, int nrow0, int ncol0) {
;     ...
;         const char* cb = smem + cur * 2 * TILE_B;
; #pragma unroll
;         for (int ks = 0; ks < 2; ++ks) {
;             bf16x8 a[4], b[4];
; #pragma unroll
;             for (int m = 0; m < 4; ++m) a[m] = *(const bf16x8*)(cb + offA[m][ks]);
; #pragma unroll
;             for (int n = 0; n < 4; ++n) b[n] = *(const bf16x8*)(cb + offB[n][ks]);
; #pragma unroll
;             for (int m = 0; m < 4; ++m)
; #pragma unroll
;                 for (int n = 0; n < 4; ++n) acc[m][n] = mfma16(b[n], a[m], acc[m][n]);
;         }
;         asm volatile("s_waitcnt vmcnt(0)" ::: "memory");
;         __syncthreads();
;     }
;     if (nvalid) { const bf16_t* qA = A + (size_t)nrow0 * K; const bf16_t* qB = Bt + (size_t)ncol0 * K; GLDS_STAGE(0, qA, qB, 0); }
; template <class Epi>
; __device__ __forceinline__ void gemm_phase(const bf16_t* A, const bf16_t* Bt, int M, int N, int K, const Epi& epi, char* smem) {
;     ...
;     for (int i = blockIdx.x; i < ntiles; i += G) {
;         const int j = i + G; const bool nv = j < ntiles;
;         gemm_tile(A, Bt, K, (i / nN) << 7, (i % nN) << 7, epi, smem, pre, nv, (j / nN) << 7, (j % nN) << 7);
	ds_read_b128 v[64:67], v142 offset:49152
	ds_read_b128 v[68:71], v139 offset:32768
	ds_read_b128 v[72:75], v142 offset:49664
	ds_read_b128 v[76:79], v142 offset:53248
	ds_read_b128 v[80:83], v142 offset:53760
	s_add_i32 s21, s21, s58
	s_waitcnt lgkmcnt(3)
	v_mfma_f32_16x16x32_bf16 v[0:3], v[64:67], v[68:71], v[0:3]
	s_cmpk_gt_i32 s21, 0x10ff
	s_cselect_b64 s[8:9], -1, 0
	s_cmpk_lt_i32 s21, 0x1100
	s_waitcnt lgkmcnt(2)
	v_mfma_f32_16x16x32_bf16 v[4:7], v[72:75], v[68:71], v[4:7]
	ds_read_b128 v[182:185], v141 offset:49152
	ds_read_b128 v[186:189], v141 offset:53760
	s_waitcnt lgkmcnt(3)
	v_mfma_f32_16x16x32_bf16 v[8:11], v[76:79], v[68:71], v[8:11]
	s_waitcnt lgkmcnt(2)
	v_mfma_f32_16x16x32_bf16 v[12:15], v[80:83], v[68:71], v[12:15]
	ds_read_b128 v[68:71], v139 offset:34816
	s_waitcnt lgkmcnt(0)
	v_mfma_f32_16x16x32_bf16 v[16:19], v[64:67], v[68:71], v[16:19]
	v_mfma_f32_16x16x32_bf16 v[20:23], v[72:75], v[68:71], v[20:23]
	v_mfma_f32_16x16x32_bf16 v[24:27], v[76:79], v[68:71], v[24:27]
	v_mfma_f32_16x16x32_bf16 v[28:31], v[80:83], v[68:71], v[28:31]
	ds_read_b128 v[68:71], v139 offset:36864
	s_waitcnt lgkmcnt(0)
	v_mfma_f32_16x16x32_bf16 v[128:131], v[64:67], v[68:71], v[32:35]
	s_nop 2
	ds_read_b128 v[32:35], v139 offset:38912
	v_mfma_f32_16x16x32_bf16 v[174:177], v[72:75], v[68:71], v[36:39]
	v_mfma_f32_16x16x32_bf16 v[178:181], v[76:79], v[68:71], v[40:43]
	v_mfma_f32_16x16x32_bf16 v[68:71], v[80:83], v[68:71], v[44:47]
	s_waitcnt lgkmcnt(0)
	v_mfma_f32_16x16x32_bf16 v[64:67], v[64:67], v[32:35], v[48:51]
	v_mfma_f32_16x16x32_bf16 v[72:75], v[72:75], v[32:35], v[52:55]
	v_mfma_f32_16x16x32_bf16 v[76:79], v[76:79], v[32:35], v[56:59]
	v_mfma_f32_16x16x32_bf16 v[80:83], v[80:83], v[32:35], v[60:63]
	ds_read_b128 v[32:35], v140 offset:32768
	s_waitcnt lgkmcnt(0)
	v_mfma_f32_16x16x32_bf16 v[56:59], v[182:185], v[32:35], v[0:3]
	s_nop 2
	ds_read_b128 v[0:3], v141 offset:49664
	s_waitcnt lgkmcnt(0)
	v_mfma_f32_16x16x32_bf16 v[60:63], v[0:3], v[32:35], v[4:7]
	s_nop 2
	ds_read_b128 v[4:7], v141 offset:53248
	s_waitcnt lgkmcnt(0)
	v_mfma_f32_16x16x32_bf16 v[48:51], v[4:7], v[32:35], v[8:11]
	s_nop 2
	ds_read_b128 v[8:11], v140 offset:34816
	v_mfma_f32_16x16x32_bf16 v[52:55], v[186:189], v[32:35], v[12:15]
	s_waitcnt lgkmcnt(0)
	v_mfma_f32_16x16x32_bf16 v[40:43], v[182:185], v[8:11], v[16:19]
	v_mfma_f32_16x16x32_bf16 v[44:47], v[0:3], v[8:11], v[20:23]
	v_mfma_f32_16x16x32_bf16 v[32:35], v[4:7], v[8:11], v[24:27]
	v_mfma_f32_16x16x32_bf16 v[36:39], v[186:189], v[8:11], v[28:31]
	ds_read_b128 v[8:11], v140 offset:36864
	s_waitcnt lgkmcnt(0)
	v_mfma_f32_16x16x32_bf16 v[20:23], v[186:189], v[8:11], v[68:71]
	s_nop 2
	ds_read_b128 v[68:71], v140 offset:38912
	s_waitcnt vmcnt(0)
	v_mfma_f32_16x16x32_bf16 v[24:27], v[182:185], v[8:11], v[128:131]
	s_waitcnt lgkmcnt(0)
	s_barrier
	v_mfma_f32_16x16x32_bf16 v[28:31], v[0:3], v[8:11], v[174:177]
	v_mfma_f32_16x16x32_bf16 v[16:19], v[4:7], v[8:11], v[178:181]
	v_mfma_f32_16x16x32_bf16 v[8:11], v[182:185], v[68:71], v[64:67]
	v_mfma_f32_16x16x32_bf16 v[12:15], v[0:3], v[68:71], v[72:75]
	v_mfma_f32_16x16x32_bf16 v[0:3], v[4:7], v[68:71], v[76:79]
	v_mfma_f32_16x16x32_bf16 v[4:7], v[186:189], v[68:71], v[80:83]
	s_cbranch_scc0 .LBB0_157
	s_mul_hi_i32 s0, s21, 0x78787879
	s_lshr_b32 s1, s0, 31
	s_ashr_i32 s0, s0, 3
	s_add_i32 s1, s0, s1
	s_lshl_b32 s0, s1, 7
	s_mul_i32 s1, s1, 17
	s_sub_i32 s1, s21, s1
	s_lshl_b32 s10, s1, 7
	s_ashr_i32 s1, s0, 31
	s_lshl_b64 s[0:1], s[0:1], 11
	v_readlane_b32 s5, v245, 53
	s_add_u32 s0, s5, s0
	v_readlane_b32 s5, v245, 54
	s_addc_u32 s1, s5, s1
	s_ashr_i32 s11, s10, 31
	s_lshl_b64 s[10:11], s[10:11], 11
	s_add_u32 s10, s56, s10
	v_readfirstlane_b32 s5, v149
	s_addc_u32 s11, s57, s11
	s_mov_b32 m0, s5
	v_readfirstlane_b32 s5, v159
	global_load_lds_dwordx4 v167, s[0:1]
	v_lshl_add_u64 v[64:65], v[84:85], 1, s[10:11]
	s_mov_b32 m0, s5
	v_readfirstlane_b32 s5, v160
	global_load_lds_dwordx4 v[64:65], off
	s_mov_b32 m0, s5
	v_readfirstlane_b32 s5, v161
	global_load_lds_dwordx4 v168, s[0:1]
	v_lshl_add_u64 v[64:65], v[86:87], 1, s[10:11]
	s_mov_b32 m0, s5
	v_readfirstlane_b32 s5, v162
	global_load_lds_dwordx4 v[64:65], off
	s_mov_b32 m0, s5
	v_readfirstlane_b32 s5, v163
	global_load_lds_dwordx4 v169, s[0:1]
	v_lshl_add_u64 v[64:65], v[88:89], 1, s[10:11]
	s_mov_b32 m0, s5
	v_readfirstlane_b32 s5, v164
	global_load_lds_dwordx4 v[64:65], off
	s_mov_b32 m0, s5
	v_lshl_add_u64 v[64:65], v[90:91], 1, s[10:11]
	global_load_lds_dwordx4 v170, s[0:1]
	v_readfirstlane_b32 s0, v165
	s_mov_b32 m0, s0
	s_nop 0
	global_load_lds_dwordx4 v[64:65], off

; __device__ __forceinline__ f32x4 mfma16(bf16x8 a, bf16x8 b, f32x4 c) { return __builtin_amdgcn_mfma_f32_16x16x32_bf16(a, b, c, 0, 0, 0); }
; template <class Epi>
; __device__ __forceinline__ void gemm_tile(const bf16_t* __restrict__ A, const bf16_t* __restrict__ Bt, int K, int row0, int col0, const Epi& epi, char* smem,
;                                           bool prefetched, bool nvalid, int nrow0, int ncol0) {
;     ...
;     for (int kt = 0; kt < nk; ++kt) {
;         const int cur = kt & 1;
;         if (kt + 1 < nk) GLDS_STAGE(cur ^ 1, pA, pB, kt + 1);
;         const char* cb = smem + cur * 2 * TILE_B;
; #pragma unroll
;         for (int ks = 0; ks < 2; ++ks) {
;             bf16x8 a[4], b[4];
; #pragma unroll
;             for (int m = 0; m < 4; ++m) a[m] = *(const bf16x8*)(cb + offA[m][ks]);
; #pragma unroll
;             for (int n = 0; n < 4; ++n) b[n] = *(const bf16x8*)(cb + offB[n][ks]);
; #pragma unroll
;             for (int m = 0; m < 4; ++m)
; #pragma unroll
;                 for (int n = 0; n < 4; ++n) acc[m][n] = mfma16(b[n], a[m], acc[m][n]);
;         }
;         asm volatile("s_waitcnt vmcnt(0)" ::: "memory");
;         __syncthreads();
;     }
.LBB0_197:
	s_and_b32 s6, s1, 0x8000
	s_xor_b32 s7, s6, 0x8000
	v_add_u32_e32 v184, s7, v149
	v_add_u32_e32 v185, 0x4000, v184
	v_readfirstlane_b32 s7, v184
	v_lshl_add_u64 v[168:169], v[106:107], 0, s[4:5]
	v_add_u32_e32 v186, 0x1000, v184
	v_readfirstlane_b32 s8, v185
	s_mov_b32 m0, s7
	v_lshl_add_u64 v[170:171], v[120:121], 0, s[4:5]
	v_add_u32_e32 v187, 0x5000, v184
	v_readfirstlane_b32 s9, v186
	global_load_lds_dwordx4 v[168:169], off
	s_mov_b32 m0, s8
	v_lshl_add_u64 v[172:173], v[108:109], 0, s[4:5]
	v_add_u32_e32 v189, 0x2000, v184
	v_readfirstlane_b32 s10, v187
	global_load_lds_dwordx4 v[170:171], off
	s_mov_b32 m0, s9
	v_lshl_add_u64 v[174:175], v[122:123], 0, s[4:5]
	v_add_u32_e32 v190, 0x6000, v184
	v_readfirstlane_b32 s11, v189
	global_load_lds_dwordx4 v[172:173], off
	s_mov_b32 m0, s10
	v_lshl_add_u64 v[176:177], v[110:111], 0, s[4:5]
	v_add_u32_e32 v191, 0x3000, v184
	v_readfirstlane_b32 s15, v190
	global_load_lds_dwordx4 v[174:175], off
	s_mov_b32 m0, s11
	v_lshl_add_u64 v[178:179], v[124:125], 0, s[4:5]
	v_add_u32_e32 v184, 0x7000, v184
	v_readfirstlane_b32 s16, v191
	global_load_lds_dwordx4 v[176:177], off
	s_mov_b32 m0, s15
	v_lshl_add_u64 v[180:181], v[118:119], 0, s[4:5]
	v_readfirstlane_b32 s17, v184
	global_load_lds_dwordx4 v[178:179], off
	s_mov_b32 m0, s16
	v_lshl_add_u64 v[182:183], v[126:127], 0, s[4:5]
	global_load_lds_dwordx4 v[180:181], off
	s_mov_b32 m0, s17
	v_or_b32_e32 v188, s6, v130
	global_load_lds_dwordx4 v[182:183], off
	v_add_u32_e32 v167, s6, v117
	ds_read_b128 v[168:171], v188 offset:16384
	ds_read_b128 v[172:175], v188 offset:16896
	ds_read_b128 v[176:179], v167
	ds_read_b128 v[180:183], v167 offset:2048
	ds_read_b128 v[184:187], v188 offset:20480
	ds_read_b128 v[188:191], v188 offset:20992
	s_waitcnt lgkmcnt(0)
	v_mfma_f32_16x16x32_bf16 v[0:3], v[168:171], v[176:179], v[0:3]
	v_or_b32_e32 v192, s6, v129
	s_add_i32 s1, s1, 0x8000
	s_add_u32 s4, s4, 0x80
	v_mfma_f32_16x16x32_bf16 v[4:7], v[172:175], v[176:179], v[4:7]
	s_addc_u32 s5, s5, 0
	s_cmpk_eq_i32 s4, 0x780
	v_mfma_f32_16x16x32_bf16 v[8:11], v[184:187], v[176:179], v[8:11]
	v_mfma_f32_16x16x32_bf16 v[12:15], v[188:191], v[176:179], v[12:15]
	v_mfma_f32_16x16x32_bf16 v[16:19], v[168:171], v[180:183], v[16:19]
	v_mfma_f32_16x16x32_bf16 v[20:23], v[172:175], v[180:183], v[20:23]
	v_mfma_f32_16x16x32_bf16 v[24:27], v[184:187], v[180:183], v[24:27]
	v_mfma_f32_16x16x32_bf16 v[28:31], v[188:191], v[180:183], v[28:31]
	ds_read_b128 v[176:179], v167 offset:4096
	ds_read_b128 v[180:183], v167 offset:6144
	v_add_u32_e32 v167, s6, v128
	s_waitcnt lgkmcnt(1)
	v_mfma_f32_16x16x32_bf16 v[32:35], v[168:171], v[176:179], v[32:35]
	v_mfma_f32_16x16x32_bf16 v[36:39], v[172:175], v[176:179], v[36:39]
	v_mfma_f32_16x16x32_bf16 v[40:43], v[184:187], v[176:179], v[40:43]
	v_mfma_f32_16x16x32_bf16 v[44:47], v[188:191], v[176:179], v[44:47]
	s_waitcnt lgkmcnt(0)
	v_mfma_f32_16x16x32_bf16 v[48:51], v[168:171], v[180:183], v[48:51]
	v_mfma_f32_16x16x32_bf16 v[52:55], v[172:175], v[180:183], v[52:55]
	ds_read_b128 v[168:171], v192 offset:16384
	ds_read_b128 v[172:175], v192 offset:16896
	v_mfma_f32_16x16x32_bf16 v[56:59], v[184:187], v[180:183], v[56:59]
	v_mfma_f32_16x16x32_bf16 v[60:63], v[188:191], v[180:183], v[60:63]
	ds_read_b128 v[176:179], v167
	ds_read_b128 v[180:183], v167 offset:2048
	ds_read_b128 v[184:187], v192 offset:20480
	ds_read_b128 v[188:191], v192 offset:20992
	s_waitcnt lgkmcnt(3)
	v_mfma_f32_16x16x32_bf16 v[0:3], v[168:171], v[176:179], v[0:3]
	v_mfma_f32_16x16x32_bf16 v[4:7], v[172:175], v[176:179], v[4:7]
	s_waitcnt lgkmcnt(1)
	v_mfma_f32_16x16x32_bf16 v[8:11], v[184:187], v[176:179], v[8:11]
	s_waitcnt lgkmcnt(0)
	v_mfma_f32_16x16x32_bf16 v[12:15], v[188:191], v[176:179], v[12:15]
	v_mfma_f32_16x16x32_bf16 v[16:19], v[168:171], v[180:183], v[16:19]
	v_mfma_f32_16x16x32_bf16 v[20:23], v[172:175], v[180:183], v[20:23]
	v_mfma_f32_16x16x32_bf16 v[24:27], v[184:187], v[180:183], v[24:27]
	v_mfma_f32_16x16x32_bf16 v[28:31], v[188:191], v[180:183], v[28:31]
	ds_read_b128 v[176:179], v167 offset:4096
	ds_read_b128 v[180:183], v167 offset:6144
	s_waitcnt vmcnt(0)
	s_waitcnt lgkmcnt(0)
	v_mfma_f32_16x16x32_bf16 v[32:35], v[168:171], v[176:179], v[32:35]
	s_barrier
	v_mfma_f32_16x16x32_bf16 v[36:39], v[172:175], v[176:179], v[36:39]
	v_mfma_f32_16x16x32_bf16 v[40:43], v[184:187], v[176:179], v[40:43]
	v_mfma_f32_16x16x32_bf16 v[44:47], v[188:191], v[176:179], v[44:47]
	v_mfma_f32_16x16x32_bf16 v[48:51], v[168:171], v[180:183], v[48:51]
	v_mfma_f32_16x16x32_bf16 v[52:55], v[172:175], v[180:183], v[52:55]
	v_mfma_f32_16x16x32_bf16 v[56:59], v[184:187], v[180:183], v[56:59]
	v_mfma_f32_16x16x32_bf16 v[60:63], v[188:191], v[180:183], v[60:63]
	s_cbranch_scc0 .LBB0_197
; __device__ __forceinline__ f32x4 mfma16(bf16x8 a, bf16x8 b, f32x4 c) { return __builtin_amdgcn_mfma_f32_16x16x32_bf16(a, b, c, 0, 0, 0); }
; template <class Epi>
; __device__ __forceinline__ void gemm_tile(const bf16_t* __restrict__ A, const bf16_t* __restrict__ Bt, int K, int row0, int col0, const Epi& epi, char* smem,
;                                           bool prefetched, bool nvalid, int nrow0, int ncol0) {
;     ...
;         const char* cb = smem + cur * 2 * TILE_B;
; #pragma unroll
;         for (int ks = 0; ks < 2; ++ks) {
;             bf16x8 a[4], b[4];
; #pragma unroll
;             for (int m = 0; m < 4; ++m) a[m] = *(const bf16x8*)(cb + offA[m][ks]);
; #pragma unroll
;             for (int n = 0; n < 4; ++n) b[n] = *(const bf16x8*)(cb + offB[n][ks]);
; #pragma unroll
;             for (int m = 0; m < 4; ++m)
; #pragma unroll
;                 for (int n = 0; n < 4; ++n) acc[m][n] = mfma16(b[n], a[m], acc[m][n]);
;         }
;         asm volatile("s_waitcnt vmcnt(0)" ::: "memory");
;         __syncthreads();
;     }
;     if (nvalid) { const bf16_t* qA = A + (size_t)nrow0 * K; const bf16_t* qB = Bt + (size_t)ncol0 * K; GLDS_STAGE(0, qA, qB, 0); }
; template <class E1, class E2>
; __device__ __forceinline__ void gemm_phase2(const bf16_t* A1, const bf16_t* B1, int M1, int N1, const E1& e1,
;                                             const bf16_t* A2, const bf16_t* B2, int M2, int N2, const E2& e2, int K, char* smem) {
;     ...
;     for (int i = (blockIdx.x + (G >> 1)) % G; i < nt2; i += G) {
;         const int j = i + G; const bool nv = j < nt2;
;         gemm_tile(A2, B2, K, (i % nM2) << 7, (i / nM2) << 7, e2, smem, pre, nv, (j % nM2) << 7, (j / nM2) << 7);
	ds_read_b128 v[106:109], v130 offset:49152
	ds_read_b128 v[118:121], v117 offset:32768
	ds_read_b128 v[122:125], v130 offset:49664
	ds_read_b128 v[168:171], v130 offset:53248
	ds_read_b128 v[172:175], v130 offset:53760
	s_add_i32 s14, s14, s58
	s_waitcnt lgkmcnt(3)
	v_mfma_f32_16x16x32_bf16 v[0:3], v[106:109], v[118:121], v[0:3]
	s_cmpk_gt_i32 s14, 0x3ff
	s_cselect_b64 s[4:5], -1, 0
	s_cmpk_lt_i32 s14, 0x400
	s_waitcnt lgkmcnt(2)
	v_mfma_f32_16x16x32_bf16 v[4:7], v[122:125], v[118:121], v[4:7]
	ds_read_b128 v[188:191], v129 offset:49152
	ds_read_b128 v[192:195], v129 offset:53248
	ds_read_b128 v[196:199], v129 offset:53760
	s_waitcnt lgkmcnt(4)
	v_mfma_f32_16x16x32_bf16 v[8:11], v[168:171], v[118:121], v[8:11]
	s_waitcnt lgkmcnt(3)
	v_mfma_f32_16x16x32_bf16 v[12:15], v[172:175], v[118:121], v[12:15]
	ds_read_b128 v[118:121], v117 offset:34816
	s_waitcnt lgkmcnt(0)
	v_mfma_f32_16x16x32_bf16 v[16:19], v[106:109], v[118:121], v[16:19]
	v_mfma_f32_16x16x32_bf16 v[20:23], v[122:125], v[118:121], v[20:23]
	v_mfma_f32_16x16x32_bf16 v[24:27], v[168:171], v[118:121], v[24:27]
	v_mfma_f32_16x16x32_bf16 v[28:31], v[172:175], v[118:121], v[28:31]
	ds_read_b128 v[118:121], v117 offset:36864
	s_waitcnt lgkmcnt(0)
	v_mfma_f32_16x16x32_bf16 v[176:179], v[106:109], v[118:121], v[32:35]
	s_nop 2
	ds_read_b128 v[32:35], v117 offset:38912
	v_mfma_f32_16x16x32_bf16 v[180:183], v[122:125], v[118:121], v[36:39]
	v_mfma_f32_16x16x32_bf16 v[184:187], v[168:171], v[118:121], v[40:43]
	v_mfma_f32_16x16x32_bf16 v[118:121], v[172:175], v[118:121], v[44:47]
	s_waitcnt lgkmcnt(0)
	v_mfma_f32_16x16x32_bf16 v[106:109], v[106:109], v[32:35], v[48:51]
	v_mfma_f32_16x16x32_bf16 v[122:125], v[122:125], v[32:35], v[52:55]
	v_mfma_f32_16x16x32_bf16 v[168:171], v[168:171], v[32:35], v[56:59]
	v_mfma_f32_16x16x32_bf16 v[172:175], v[172:175], v[32:35], v[60:63]
	ds_read_b128 v[32:35], v128 offset:32768
	s_waitcnt lgkmcnt(0)
	v_mfma_f32_16x16x32_bf16 v[56:59], v[188:191], v[32:35], v[0:3]
	s_nop 2
	ds_read_b128 v[0:3], v129 offset:49664
	s_waitcnt lgkmcnt(0)
	v_mfma_f32_16x16x32_bf16 v[60:63], v[0:3], v[32:35], v[4:7]
	s_nop 2
	ds_read_b128 v[4:7], v128 offset:34816
	v_mfma_f32_16x16x32_bf16 v[48:51], v[192:195], v[32:35], v[8:11]
	v_mfma_f32_16x16x32_bf16 v[52:55], v[196:199], v[32:35], v[12:15]
	s_nop 2
	ds_read_b128 v[12:15], v128 offset:38912
	s_waitcnt lgkmcnt(1)
	v_mfma_f32_16x16x32_bf16 v[44:47], v[188:191], v[4:7], v[16:19]
	v_mfma_f32_16x16x32_bf16 v[40:43], v[0:3], v[4:7], v[20:23]
	v_mfma_f32_16x16x32_bf16 v[36:39], v[192:195], v[4:7], v[24:27]
	v_mfma_f32_16x16x32_bf16 v[32:35], v[196:199], v[4:7], v[28:31]
	ds_read_b128 v[4:7], v128 offset:36864
	s_waitcnt vmcnt(0)
	s_waitcnt lgkmcnt(0)
	v_mfma_f32_16x16x32_bf16 v[28:31], v[188:191], v[4:7], v[176:179]
	s_barrier
	v_mfma_f32_16x16x32_bf16 v[24:27], v[0:3], v[4:7], v[180:183]
	v_mfma_f32_16x16x32_bf16 v[20:23], v[192:195], v[4:7], v[184:187]
	v_mfma_f32_16x16x32_bf16 v[16:19], v[196:199], v[4:7], v[118:121]
	v_mfma_f32_16x16x32_bf16 v[4:7], v[188:191], v[12:15], v[106:109]
	v_mfma_f32_16x16x32_bf16 v[8:11], v[0:3], v[12:15], v[122:125]
	v_mfma_f32_16x16x32_bf16 v[0:3], v[192:195], v[12:15], v[168:171]
	v_mfma_f32_16x16x32_bf16 v[12:15], v[196:199], v[12:15], v[172:175]
	s_cbranch_scc0 .LBB0_191
	s_ashr_i32 s1, s14, 31
	s_lshr_b32 s1, s1, 30
	s_add_i32 s1, s14, s1
	s_and_b32 s6, s1, 0x1fffffc
	s_sub_i32 s6, s14, s6
	s_lshl_b32 s6, s6, 7
	s_lshl_b32 s1, s1, 5
	s_ashr_i32 s7, s6, 31
	s_and_b32 s8, s1, 0xffffff80
	s_lshl_b64 s[6:7], s[6:7], 11
	s_add_u32 s6, s12, s6
	s_addc_u32 s7, s13, s7
	s_ashr_i32 s9, s8, 31
	s_lshl_b64 s[8:9], s[8:9], 11
	v_readlane_b32 s1, v245, 53
	s_add_u32 s8, s1, s8
	v_readlane_b32 s1, v245, 54
	s_addc_u32 s9, s1, s9
	v_readfirstlane_b32 s1, v149
	s_mov_b32 m0, s1
	v_readfirstlane_b32 s1, v131
	global_load_lds_dwordx4 v163, s[6:7]
	v_lshl_add_u64 v[106:107], v[64:65], 1, s[8:9]
	s_mov_b32 m0, s1
	v_readfirstlane_b32 s1, v139
	global_load_lds_dwordx4 v[106:107], off
	s_mov_b32 m0, s1
	v_readfirstlane_b32 s1, v140
	global_load_lds_dwordx4 v164, s[6:7]
	v_lshl_add_u64 v[106:107], v[66:67], 1, s[8:9]
	s_mov_b32 m0, s1
	v_readfirstlane_b32 s1, v141
	global_load_lds_dwordx4 v[106:107], off
	s_mov_b32 m0, s1
	v_readfirstlane_b32 s1, v142
	global_load_lds_dwordx4 v165, s[6:7]
	v_lshl_add_u64 v[106:107], v[68:69], 1, s[8:9]
	s_mov_b32 m0, s1
	v_readfirstlane_b32 s1, v143
	global_load_lds_dwordx4 v[106:107], off
	s_mov_b32 m0, s1
	v_readfirstlane_b32 s1, v144
	global_load_lds_dwordx4 v166, s[6:7]
	v_lshl_add_u64 v[106:107], v[70:71], 1, s[8:9]
	s_mov_b32 m0, s1
	s_nop 0
	global_load_lds_dwordx4 v[106:107], off
	s_branch .LBB0_191

; __device__ __forceinline__ f32x4 mfma16(bf16x8 a, bf16x8 b, f32x4 c) { return __builtin_amdgcn_mfma_f32_16x16x32_bf16(a, b, c, 0, 0, 0); }
; template <class Epi>
; __device__ __forceinline__ void gemm_tile(const bf16_t* __restrict__ A, const bf16_t* __restrict__ Bt, int K, int row0, int col0, const Epi& epi, char* smem,
;                                           bool prefetched, bool nvalid, int nrow0, int ncol0) {
;     ...
;     for (int kt = 0; kt < nk; ++kt) {
;         const int cur = kt & 1;
;         if (kt + 1 < nk) GLDS_STAGE(cur ^ 1, pA, pB, kt + 1);
;         const char* cb = smem + cur * 2 * TILE_B;
; #pragma unroll
;         for (int ks = 0; ks < 2; ++ks) {
;             bf16x8 a[4], b[4];
; #pragma unroll
;             for (int m = 0; m < 4; ++m) a[m] = *(const bf16x8*)(cb + offA[m][ks]);
; #pragma unroll
;             for (int n = 0; n < 4; ++n) b[n] = *(const bf16x8*)(cb + offB[n][ks]);
; #pragma unroll
;             for (int m = 0; m < 4; ++m)
; #pragma unroll
;                 for (int n = 0; n < 4; ++n) acc[m][n] = mfma16(b[n], a[m], acc[m][n]);
;         }
;         asm volatile("s_waitcnt vmcnt(0)" ::: "memory");
;         __syncthreads();
;     }
.LBB0_460:
	s_and_b32 s5, s1, 0x8000
	s_xor_b32 s8, s5, 0x8000
	v_add_u32_e32 v172, s8, v149
	v_add_u32_e32 v173, 0x4000, v172
	v_readfirstlane_b32 s8, v172
	v_lshl_add_u64 v[130:131], v[94:95], 0, s[6:7]
	v_add_u32_e32 v174, 0x1000, v172
	v_readfirstlane_b32 s9, v173
	s_mov_b32 m0, s8
	v_lshl_add_u64 v[142:143], v[102:103], 0, s[6:7]
	v_add_u32_e32 v175, 0x5000, v172
	v_readfirstlane_b32 s10, v174
	global_load_lds_dwordx4 v[130:131], off
	s_mov_b32 m0, s9
	v_lshl_add_u64 v[144:145], v[96:97], 0, s[6:7]
	v_add_u32_e32 v176, 0x2000, v172
	v_readfirstlane_b32 s11, v175
	global_load_lds_dwordx4 v[142:143], off
	s_mov_b32 m0, s10
	v_lshl_add_u64 v[162:163], v[104:105], 0, s[6:7]
	v_add_u32_e32 v177, 0x6000, v172
	v_readfirstlane_b32 s12, v176
	global_load_lds_dwordx4 v[144:145], off
	s_mov_b32 m0, s11
	v_lshl_add_u64 v[164:165], v[98:99], 0, s[6:7]
	v_add_u32_e32 v179, 0x3000, v172
	v_readfirstlane_b32 s13, v177
	global_load_lds_dwordx4 v[162:163], off
	s_mov_b32 m0, s12
	v_lshl_add_u64 v[166:167], v[106:107], 0, s[6:7]
	v_add_u32_e32 v172, 0x7000, v172
	v_readfirstlane_b32 s17, v179
	global_load_lds_dwordx4 v[164:165], off
	s_mov_b32 m0, s13
	v_lshl_add_u64 v[168:169], v[100:101], 0, s[6:7]
	v_readfirstlane_b32 s18, v172
	global_load_lds_dwordx4 v[166:167], off
	s_mov_b32 m0, s17
	v_lshl_add_u64 v[170:171], v[108:109], 0, s[6:7]
	global_load_lds_dwordx4 v[168:169], off
	s_mov_b32 m0, s18
	v_or_b32_e32 v178, s5, v87
	global_load_lds_dwordx4 v[170:171], off
	v_add_u32_e32 v141, s5, v110
	ds_read_b128 v[142:145], v178 offset:16384
	ds_read_b128 v[162:165], v178 offset:16896
	ds_read_b128 v[166:169], v141
	ds_read_b128 v[170:173], v141 offset:2048
	ds_read_b128 v[174:177], v178 offset:20480
	ds_read_b128 v[178:181], v178 offset:20992
	s_waitcnt lgkmcnt(0)
	v_mfma_f32_16x16x32_bf16 v[0:3], v[142:145], v[166:169], v[0:3]
	v_add_u32_e32 v130, s5, v111
	v_or_b32_e32 v131, s5, v118
	s_add_u32 s6, s6, 0x80
	v_mfma_f32_16x16x32_bf16 v[4:7], v[162:165], v[166:169], v[4:7]
	s_addc_u32 s7, s7, 0
	s_add_i32 s1, s1, 0x8000
	s_cmpk_eq_i32 s6, 0x780
	v_mfma_f32_16x16x32_bf16 v[8:11], v[174:177], v[166:169], v[8:11]
	v_mfma_f32_16x16x32_bf16 v[12:15], v[178:181], v[166:169], v[12:15]
	v_mfma_f32_16x16x32_bf16 v[16:19], v[142:145], v[170:173], v[16:19]
	v_mfma_f32_16x16x32_bf16 v[20:23], v[162:165], v[170:173], v[20:23]
	v_mfma_f32_16x16x32_bf16 v[24:27], v[174:177], v[170:173], v[24:27]
	v_mfma_f32_16x16x32_bf16 v[28:31], v[178:181], v[170:173], v[28:31]
	ds_read_b128 v[166:169], v141 offset:4096
	ds_read_b128 v[170:173], v141 offset:6144
	s_waitcnt lgkmcnt(1)
	v_mfma_f32_16x16x32_bf16 v[32:35], v[142:145], v[166:169], v[32:35]
	v_mfma_f32_16x16x32_bf16 v[36:39], v[162:165], v[166:169], v[36:39]
	v_mfma_f32_16x16x32_bf16 v[40:43], v[174:177], v[166:169], v[40:43]
	v_mfma_f32_16x16x32_bf16 v[44:47], v[178:181], v[166:169], v[44:47]
	s_waitcnt lgkmcnt(0)
	v_mfma_f32_16x16x32_bf16 v[48:51], v[142:145], v[170:173], v[48:51]
	v_mfma_f32_16x16x32_bf16 v[52:55], v[162:165], v[170:173], v[52:55]
	ds_read_b128 v[142:145], v131 offset:16384
	ds_read_b128 v[162:165], v131 offset:16896
	v_mfma_f32_16x16x32_bf16 v[56:59], v[174:177], v[170:173], v[56:59]
	v_mfma_f32_16x16x32_bf16 v[60:63], v[178:181], v[170:173], v[60:63]
	ds_read_b128 v[166:169], v130
	ds_read_b128 v[170:173], v130 offset:2048
	ds_read_b128 v[174:177], v131 offset:20480
	ds_read_b128 v[178:181], v131 offset:20992
	s_waitcnt lgkmcnt(3)
	v_mfma_f32_16x16x32_bf16 v[0:3], v[142:145], v[166:169], v[0:3]
	v_mfma_f32_16x16x32_bf16 v[4:7], v[162:165], v[166:169], v[4:7]
	s_waitcnt lgkmcnt(1)
	v_mfma_f32_16x16x32_bf16 v[8:11], v[174:177], v[166:169], v[8:11]
	s_waitcnt lgkmcnt(0)
	v_mfma_f32_16x16x32_bf16 v[12:15], v[178:181], v[166:169], v[12:15]
	v_mfma_f32_16x16x32_bf16 v[16:19], v[142:145], v[170:173], v[16:19]
	v_mfma_f32_16x16x32_bf16 v[20:23], v[162:165], v[170:173], v[20:23]
	v_mfma_f32_16x16x32_bf16 v[24:27], v[174:177], v[170:173], v[24:27]
	v_mfma_f32_16x16x32_bf16 v[28:31], v[178:181], v[170:173], v[28:31]
	ds_read_b128 v[166:169], v130 offset:4096
	ds_read_b128 v[170:173], v130 offset:6144
	s_waitcnt vmcnt(0)
	s_waitcnt lgkmcnt(0)
	v_mfma_f32_16x16x32_bf16 v[32:35], v[142:145], v[166:169], v[32:35]
	s_barrier
	v_mfma_f32_16x16x32_bf16 v[36:39], v[162:165], v[166:169], v[36:39]
	v_mfma_f32_16x16x32_bf16 v[40:43], v[174:177], v[166:169], v[40:43]
	v_mfma_f32_16x16x32_bf16 v[44:47], v[178:181], v[166:169], v[44:47]
	v_mfma_f32_16x16x32_bf16 v[48:51], v[142:145], v[170:173], v[48:51]
	v_mfma_f32_16x16x32_bf16 v[52:55], v[162:165], v[170:173], v[52:55]
	v_mfma_f32_16x16x32_bf16 v[56:59], v[174:177], v[170:173], v[56:59]
	v_mfma_f32_16x16x32_bf16 v[60:63], v[178:181], v[170:173], v[60:63]
	s_cbranch_scc0 .LBB0_460
; __device__ __forceinline__ f32x4 mfma16(bf16x8 a, bf16x8 b, f32x4 c) { return __builtin_amdgcn_mfma_f32_16x16x32_bf16(a, b, c, 0, 0, 0); }
; template <class Epi>
; __device__ __forceinline__ void gemm_tile(const bf16_t* __restrict__ A, const bf16_t* __restrict__ Bt, int K, int row0, int col0, const Epi& epi, char* smem,
;                                           bool prefetched, bool nvalid, int nrow0, int ncol0) {
;     ...
;         const char* cb = smem + cur * 2 * TILE_B;
; #pragma unroll
;         for (int ks = 0; ks < 2; ++ks) {
;             bf16x8 a[4], b[4];
; #pragma unroll
;             for (int m = 0; m < 4; ++m) a[m] = *(const bf16x8*)(cb + offA[m][ks]);
; #pragma unroll
;             for (int n = 0; n < 4; ++n) b[n] = *(const bf16x8*)(cb + offB[n][ks]);
; #pragma unroll
;             for (int m = 0; m < 4; ++m)
; #pragma unroll
;                 for (int n = 0; n < 4; ++n) acc[m][n] = mfma16(b[n], a[m], acc[m][n]);
;         }
;         asm volatile("s_waitcnt vmcnt(0)" ::: "memory");
;         __syncthreads();
;     }
;     if (nvalid) { const bf16_t* qA = A + (size_t)nrow0 * K; const bf16_t* qB = Bt + (size_t)ncol0 * K; GLDS_STAGE(0, qA, qB, 0); }
; template <class Epi>
; __device__ __forceinline__ void gemm_phase(const bf16_t* A, const bf16_t* Bt, int M, int N, int K, const Epi& epi, char* smem) {
;     ...
;     for (int i = blockIdx.x; i < ntiles; i += G) {
;         const int j = i + G; const bool nv = j < ntiles;
;         gemm_tile(A, Bt, K, (i / nN) << 7, (i % nN) << 7, epi, smem, pre, nv, (j / nN) << 7, (j % nN) << 7);
	ds_read_b128 v[94:97], v87 offset:49152
	ds_read_b128 v[98:101], v87 offset:49664
	ds_read_b128 v[102:105], v110 offset:32768
	ds_read_b128 v[106:109], v110 offset:34816
	ds_read_b128 v[142:145], v87 offset:53248
	ds_read_b128 v[162:165], v87 offset:53760
	s_add_i32 s16, s16, s58
	s_waitcnt lgkmcnt(3)
	v_mfma_f32_16x16x32_bf16 v[0:3], v[94:97], v[102:105], v[0:3]
	s_cmpk_gt_i32 s16, 0x7ff
	s_cselect_b64 s[6:7], -1, 0
	s_cmpk_lt_i32 s16, 0x800
	v_mfma_f32_16x16x32_bf16 v[4:7], v[98:101], v[102:105], v[4:7]
	s_waitcnt lgkmcnt(1)
	v_mfma_f32_16x16x32_bf16 v[8:11], v[142:145], v[102:105], v[8:11]
	s_waitcnt lgkmcnt(0)
	v_mfma_f32_16x16x32_bf16 v[12:15], v[162:165], v[102:105], v[12:15]
	v_mfma_f32_16x16x32_bf16 v[16:19], v[94:97], v[106:109], v[16:19]
	v_mfma_f32_16x16x32_bf16 v[20:23], v[98:101], v[106:109], v[20:23]
	v_mfma_f32_16x16x32_bf16 v[24:27], v[142:145], v[106:109], v[24:27]
	v_mfma_f32_16x16x32_bf16 v[28:31], v[162:165], v[106:109], v[28:31]
	ds_read_b128 v[102:105], v110 offset:36864
	ds_read_b128 v[106:109], v110 offset:38912
	ds_read_b128 v[178:181], v118 offset:49152
	s_waitcnt lgkmcnt(2)
	v_mfma_f32_16x16x32_bf16 v[166:169], v[94:97], v[102:105], v[32:35]
	v_mfma_f32_16x16x32_bf16 v[170:173], v[98:101], v[102:105], v[36:39]
	v_mfma_f32_16x16x32_bf16 v[174:177], v[142:145], v[102:105], v[40:43]
	v_mfma_f32_16x16x32_bf16 v[102:105], v[162:165], v[102:105], v[44:47]
	s_waitcnt lgkmcnt(1)
	v_mfma_f32_16x16x32_bf16 v[94:97], v[94:97], v[106:109], v[48:51]
	v_mfma_f32_16x16x32_bf16 v[98:101], v[98:101], v[106:109], v[52:55]
	v_mfma_f32_16x16x32_bf16 v[142:145], v[142:145], v[106:109], v[56:59]
	v_mfma_f32_16x16x32_bf16 v[106:109], v[162:165], v[106:109], v[60:63]
	ds_read_b128 v[162:165], v118 offset:49664
	ds_read_b128 v[32:35], v111 offset:32768
	ds_read_b128 v[36:39], v111 offset:34816
	ds_read_b128 v[182:185], v118 offset:53760
	s_waitcnt lgkmcnt(2)
	v_mfma_f32_16x16x32_bf16 v[52:55], v[178:181], v[32:35], v[0:3]
	s_nop 2
	ds_read_b128 v[0:3], v118 offset:53248
	v_mfma_f32_16x16x32_bf16 v[56:59], v[162:165], v[32:35], v[4:7]
	s_nop 2
	ds_read_b128 v[4:7], v111 offset:36864
	ds_read_b128 v[186:189], v111 offset:38912
	s_waitcnt vmcnt(0)
	s_waitcnt lgkmcnt(0)
	v_mfma_f32_16x16x32_bf16 v[60:63], v[0:3], v[32:35], v[8:11]
	s_barrier
	v_mfma_f32_16x16x32_bf16 v[48:51], v[182:185], v[32:35], v[12:15]
	v_mfma_f32_16x16x32_bf16 v[44:47], v[178:181], v[36:39], v[16:19]
	v_mfma_f32_16x16x32_bf16 v[40:43], v[162:165], v[36:39], v[20:23]
	v_mfma_f32_16x16x32_bf16 v[32:35], v[0:3], v[36:39], v[24:27]
	v_mfma_f32_16x16x32_bf16 v[24:27], v[182:185], v[36:39], v[28:31]
	v_mfma_f32_16x16x32_bf16 v[36:39], v[178:181], v[4:7], v[166:169]
	v_mfma_f32_16x16x32_bf16 v[28:31], v[162:165], v[4:7], v[170:173]
	v_mfma_f32_16x16x32_bf16 v[20:23], v[0:3], v[4:7], v[174:177]
	v_mfma_f32_16x16x32_bf16 v[16:19], v[182:185], v[4:7], v[102:105]
	v_mfma_f32_16x16x32_bf16 v[12:15], v[178:181], v[186:189], v[94:97]
	v_mfma_f32_16x16x32_bf16 v[8:11], v[162:165], v[186:189], v[98:101]
	v_mfma_f32_16x16x32_bf16 v[4:7], v[0:3], v[186:189], v[142:145]
	v_mfma_f32_16x16x32_bf16 v[0:3], v[182:185], v[186:189], v[106:109]
	s_cbranch_scc0 .LBB0_454
	s_ashr_i32 s1, s16, 31
	s_lshr_b32 s1, s1, 29
	s_add_i32 s1, s16, s1
	s_lshl_b32 s5, s1, 4
	s_and_b32 s8, s5, 0xffffff80
	s_and_b32 s1, s1, 0x1fffff8
	s_sub_i32 s1, s16, s1
	s_ashr_i32 s9, s8, 31
	s_lshl_b32 s10, s1, 7
	s_lshl_b64 s[8:9], s[8:9], 11
	v_readlane_b32 s12, v245, 60
	v_readlane_b32 s13, v245, 61
	s_add_u32 s8, s12, s8
	s_addc_u32 s9, s13, s9
	s_ashr_i32 s11, s10, 31
	s_lshl_b64 s[10:11], s[10:11], 11
	s_add_u32 s10, s14, s10
	v_readfirstlane_b32 s1, v149
	s_addc_u32 s11, s15, s11
	s_mov_b32 m0, s1
	v_readfirstlane_b32 s1, v119
	global_load_lds_dwordx4 v126, s[8:9]
	v_lshl_add_u64 v[94:95], v[64:65], 1, s[10:11]
	s_mov_b32 m0, s1
	v_readfirstlane_b32 s1, v120
	global_load_lds_dwordx4 v[94:95], off
	s_mov_b32 m0, s1
	v_readfirstlane_b32 s1, v121
	global_load_lds_dwordx4 v127, s[8:9]
	v_lshl_add_u64 v[94:95], v[66:67], 1, s[10:11]
	s_mov_b32 m0, s1
	v_readfirstlane_b32 s1, v122
	global_load_lds_dwordx4 v[94:95], off
	s_mov_b32 m0, s1
	v_readfirstlane_b32 s1, v123
	global_load_lds_dwordx4 v128, s[8:9]
	v_lshl_add_u64 v[94:95], v[68:69], 1, s[10:11]
	s_mov_b32 m0, s1
	v_readfirstlane_b32 s1, v124
	global_load_lds_dwordx4 v[94:95], off
	s_mov_b32 m0, s1
	v_readfirstlane_b32 s1, v125
	global_load_lds_dwordx4 v129, s[8:9]
	v_lshl_add_u64 v[94:95], v[70:71], 1, s[10:11]
	s_mov_b32 m0, s1
	s_nop 0
	global_load_lds_dwordx4 v[94:95], off
	s_branch .LBB0_454

; __device__ __forceinline__ f32x4 mfma16(bf16x8 a, bf16x8 b, f32x4 c) { return __builtin_amdgcn_mfma_f32_16x16x32_bf16(a, b, c, 0, 0, 0); }
; template <class Epi>
; __device__ __forceinline__ void gemm_tile(const bf16_t* __restrict__ A, const bf16_t* __restrict__ Bt, int K, int row0, int col0, const Epi& epi, char* smem,
;                                           bool prefetched, bool nvalid, int nrow0, int ncol0) {
;     ...
;     for (int kt = 0; kt < nk; ++kt) {
;         const int cur = kt & 1;
;         if (kt + 1 < nk) GLDS_STAGE(cur ^ 1, pA, pB, kt + 1);
;         const char* cb = smem + cur * 2 * TILE_B;
; #pragma unroll
;         for (int ks = 0; ks < 2; ++ks) {
;             bf16x8 a[4], b[4];
; #pragma unroll
;             for (int m = 0; m < 4; ++m) a[m] = *(const bf16x8*)(cb + offA[m][ks]);
; #pragma unroll
;             for (int n = 0; n < 4; ++n) b[n] = *(const bf16x8*)(cb + offB[n][ks]);
; #pragma unroll
;             for (int m = 0; m < 4; ++m)
; #pragma unroll
;                 for (int n = 0; n < 4; ++n) acc[m][n] = mfma16(b[n], a[m], acc[m][n]);
;         }
;         asm volatile("s_waitcnt vmcnt(0)" ::: "memory");
;         __syncthreads();
;     }
.LBB0_563:
	s_and_b32 s9, s8, 0x8000
	s_xor_b32 s10, s9, 0x8000
	v_add_u32_e32 v188, s10, v149
	v_add_u32_e32 v189, 0x4000, v188
	v_readfirstlane_b32 s10, v188
	v_lshl_add_u64 v[172:173], v[110:111], 0, s[6:7]
	v_add_u32_e32 v190, 0x1000, v188
	v_readfirstlane_b32 s11, v189
	s_mov_b32 m0, s10
	v_lshl_add_u64 v[174:175], v[124:125], 0, s[6:7]
	v_add_u32_e32 v191, 0x5000, v188
	v_readfirstlane_b32 s12, v190
	global_load_lds_dwordx4 v[172:173], off
	s_mov_b32 m0, s11
	v_lshl_add_u64 v[176:177], v[118:119], 0, s[6:7]
	v_add_u32_e32 v193, 0x2000, v188
	v_readfirstlane_b32 s13, v191
	global_load_lds_dwordx4 v[174:175], off
	s_mov_b32 m0, s12
	v_lshl_add_u64 v[178:179], v[126:127], 0, s[6:7]
	v_add_u32_e32 v194, 0x6000, v188
	v_readfirstlane_b32 s17, v193
	global_load_lds_dwordx4 v[176:177], off
	s_mov_b32 m0, s13
	v_lshl_add_u64 v[180:181], v[120:121], 0, s[6:7]
	v_add_u32_e32 v195, 0x3000, v188
	v_readfirstlane_b32 s18, v194
	global_load_lds_dwordx4 v[178:179], off
	s_mov_b32 m0, s17
	v_lshl_add_u64 v[182:183], v[128:129], 0, s[6:7]
	v_add_u32_e32 v188, 0x7000, v188
	v_readfirstlane_b32 s19, v195
	global_load_lds_dwordx4 v[180:181], off
	s_mov_b32 m0, s18
	v_lshl_add_u64 v[184:185], v[122:123], 0, s[6:7]
	v_readfirstlane_b32 s20, v188
	global_load_lds_dwordx4 v[182:183], off
	s_mov_b32 m0, s19
	v_lshl_add_u64 v[186:187], v[130:131], 0, s[6:7]
	global_load_lds_dwordx4 v[184:185], off
	s_mov_b32 m0, s20
	v_or_b32_e32 v192, s9, v142
	global_load_lds_dwordx4 v[186:187], off
	v_add_u32_e32 v196, s9, v85
	ds_read_b128 v[172:175], v192 offset:16384
	ds_read_b128 v[176:179], v192 offset:16896
	ds_read_b128 v[180:183], v196
	ds_read_b128 v[184:187], v196 offset:2048
	ds_read_b128 v[188:191], v192 offset:20480
	ds_read_b128 v[192:195], v192 offset:20992
	s_waitcnt lgkmcnt(0)
	v_mfma_f32_16x16x32_bf16 v[0:3], v[172:175], v[180:183], v[0:3]
	v_or_b32_e32 v197, s9, v141
	s_add_i32 s8, s8, 0x8000
	s_add_u32 s6, s6, 0x80
	v_mfma_f32_16x16x32_bf16 v[4:7], v[176:179], v[180:183], v[4:7]
	s_addc_u32 s7, s7, 0
	s_cmpk_eq_i32 s6, 0x780
	v_mfma_f32_16x16x32_bf16 v[8:11], v[188:191], v[180:183], v[8:11]
	v_mfma_f32_16x16x32_bf16 v[12:15], v[192:195], v[180:183], v[12:15]
	v_mfma_f32_16x16x32_bf16 v[16:19], v[172:175], v[184:187], v[16:19]
	v_mfma_f32_16x16x32_bf16 v[20:23], v[176:179], v[184:187], v[20:23]
	v_mfma_f32_16x16x32_bf16 v[24:27], v[188:191], v[184:187], v[24:27]
	v_mfma_f32_16x16x32_bf16 v[28:31], v[192:195], v[184:187], v[28:31]
	ds_read_b128 v[180:183], v196 offset:4096
	ds_read_b128 v[184:187], v196 offset:6144
	v_add_u32_e32 v196, s9, v87
	s_waitcnt lgkmcnt(1)
	v_mfma_f32_16x16x32_bf16 v[32:35], v[172:175], v[180:183], v[32:35]
	v_mfma_f32_16x16x32_bf16 v[36:39], v[176:179], v[180:183], v[36:39]
	v_mfma_f32_16x16x32_bf16 v[40:43], v[188:191], v[180:183], v[40:43]
	v_mfma_f32_16x16x32_bf16 v[44:47], v[192:195], v[180:183], v[44:47]
	s_waitcnt lgkmcnt(0)
	v_mfma_f32_16x16x32_bf16 v[48:51], v[172:175], v[184:187], v[48:51]
	v_mfma_f32_16x16x32_bf16 v[52:55], v[176:179], v[184:187], v[52:55]
	ds_read_b128 v[172:175], v197 offset:16384
	ds_read_b128 v[176:179], v197 offset:16896
	v_mfma_f32_16x16x32_bf16 v[56:59], v[188:191], v[184:187], v[56:59]
	v_mfma_f32_16x16x32_bf16 v[60:63], v[192:195], v[184:187], v[60:63]
	ds_read_b128 v[180:183], v196
	ds_read_b128 v[184:187], v196 offset:2048
	ds_read_b128 v[188:191], v197 offset:20480
	ds_read_b128 v[192:195], v197 offset:20992
	s_waitcnt lgkmcnt(3)
	v_mfma_f32_16x16x32_bf16 v[0:3], v[172:175], v[180:183], v[0:3]
	v_mfma_f32_16x16x32_bf16 v[4:7], v[176:179], v[180:183], v[4:7]
	s_waitcnt lgkmcnt(1)
	v_mfma_f32_16x16x32_bf16 v[8:11], v[188:191], v[180:183], v[8:11]
	s_waitcnt lgkmcnt(0)
	v_mfma_f32_16x16x32_bf16 v[12:15], v[192:195], v[180:183], v[12:15]
	v_mfma_f32_16x16x32_bf16 v[16:19], v[172:175], v[184:187], v[16:19]
	v_mfma_f32_16x16x32_bf16 v[20:23], v[176:179], v[184:187], v[20:23]
	v_mfma_f32_16x16x32_bf16 v[24:27], v[188:191], v[184:187], v[24:27]
	v_mfma_f32_16x16x32_bf16 v[28:31], v[192:195], v[184:187], v[28:31]
	ds_read_b128 v[180:183], v196 offset:4096
	ds_read_b128 v[184:187], v196 offset:6144
	s_waitcnt vmcnt(0)
	s_waitcnt lgkmcnt(0)
	v_mfma_f32_16x16x32_bf16 v[32:35], v[172:175], v[180:183], v[32:35]
	s_barrier
	v_mfma_f32_16x16x32_bf16 v[36:39], v[176:179], v[180:183], v[36:39]
	v_mfma_f32_16x16x32_bf16 v[40:43], v[188:191], v[180:183], v[40:43]
	v_mfma_f32_16x16x32_bf16 v[44:47], v[192:195], v[180:183], v[44:47]
	v_mfma_f32_16x16x32_bf16 v[48:51], v[172:175], v[184:187], v[48:51]
	v_mfma_f32_16x16x32_bf16 v[52:55], v[176:179], v[184:187], v[52:55]
	v_mfma_f32_16x16x32_bf16 v[56:59], v[188:191], v[184:187], v[56:59]
	v_mfma_f32_16x16x32_bf16 v[60:63], v[192:195], v[184:187], v[60:63]
	s_cbranch_scc0 .LBB0_563
; __device__ __forceinline__ f32x4 mfma16(bf16x8 a, bf16x8 b, f32x4 c) { return __builtin_amdgcn_mfma_f32_16x16x32_bf16(a, b, c, 0, 0, 0); }
; template <class Epi>
; __device__ __forceinline__ void gemm_tile(const bf16_t* __restrict__ A, const bf16_t* __restrict__ Bt, int K, int row0, int col0, const Epi& epi, char* smem,
;                                           bool prefetched, bool nvalid, int nrow0, int ncol0) {
;     ...
;         const char* cb = smem + cur * 2 * TILE_B;
; #pragma unroll
;         for (int ks = 0; ks < 2; ++ks) {
;             bf16x8 a[4], b[4];
; #pragma unroll
;             for (int m = 0; m < 4; ++m) a[m] = *(const bf16x8*)(cb + offA[m][ks]);
; #pragma unroll
;             for (int n = 0; n < 4; ++n) b[n] = *(const bf16x8*)(cb + offB[n][ks]);
; #pragma unroll
;             for (int m = 0; m < 4; ++m)
; #pragma unroll
;                 for (int n = 0; n < 4; ++n) acc[m][n] = mfma16(b[n], a[m], acc[m][n]);
;         }
;         asm volatile("s_waitcnt vmcnt(0)" ::: "memory");
;         __syncthreads();
;     }
;     if (nvalid) { const bf16_t* qA = A + (size_t)nrow0 * K; const bf16_t* qB = Bt + (size_t)ncol0 * K; GLDS_STAGE(0, qA, qB, 0); }
; template <class Epi>
; __device__ __forceinline__ void gemm_phase(const bf16_t* A, const bf16_t* Bt, int M, int N, int K, const Epi& epi, char* smem) {
;     ...
;     for (int i = blockIdx.x; i < ntiles; i += G) {
;         const int j = i + G; const bool nv = j < ntiles;
;         gemm_tile(A, Bt, K, (i / nN) << 7, (i % nN) << 7, epi, smem, pre, nv, (j / nN) << 7, (j % nN) << 7);
	ds_read_b128 v[118:121], v142 offset:49152
	ds_read_b128 v[122:125], v85 offset:32768
	ds_read_b128 v[126:129], v142 offset:49664
	ds_read_b128 v[172:175], v142 offset:53248
	ds_read_b128 v[176:179], v142 offset:53760
	s_add_i32 s16, s16, s58
	s_waitcnt lgkmcnt(3)
	v_mfma_f32_16x16x32_bf16 v[0:3], v[118:121], v[122:125], v[0:3]
	s_cmpk_gt_i32 s16, 0x1fff
	s_cselect_b64 s[6:7], -1, 0
	s_cmpk_lt_i32 s16, 0x2000
	s_waitcnt lgkmcnt(2)
	v_mfma_f32_16x16x32_bf16 v[4:7], v[126:129], v[122:125], v[4:7]
	ds_read_b128 v[192:195], v141 offset:49152
	ds_read_b128 v[196:199], v141 offset:53760
	s_waitcnt lgkmcnt(3)
	v_mfma_f32_16x16x32_bf16 v[8:11], v[172:175], v[122:125], v[8:11]
	s_waitcnt lgkmcnt(2)
	v_mfma_f32_16x16x32_bf16 v[12:15], v[176:179], v[122:125], v[12:15]
	ds_read_b128 v[122:125], v85 offset:34816
	s_waitcnt lgkmcnt(0)
	v_mfma_f32_16x16x32_bf16 v[16:19], v[118:121], v[122:125], v[16:19]
	v_mfma_f32_16x16x32_bf16 v[20:23], v[126:129], v[122:125], v[20:23]
	v_mfma_f32_16x16x32_bf16 v[24:27], v[172:175], v[122:125], v[24:27]
	v_mfma_f32_16x16x32_bf16 v[28:31], v[176:179], v[122:125], v[28:31]
	ds_read_b128 v[122:125], v85 offset:36864
	s_waitcnt lgkmcnt(0)
	v_mfma_f32_16x16x32_bf16 v[180:183], v[118:121], v[122:125], v[32:35]
	s_nop 2
	ds_read_b128 v[32:35], v85 offset:38912
	v_mfma_f32_16x16x32_bf16 v[184:187], v[126:129], v[122:125], v[36:39]
	v_mfma_f32_16x16x32_bf16 v[188:191], v[172:175], v[122:125], v[40:43]
	v_mfma_f32_16x16x32_bf16 v[122:125], v[176:179], v[122:125], v[44:47]
	s_waitcnt lgkmcnt(0)
	v_mfma_f32_16x16x32_bf16 v[118:121], v[118:121], v[32:35], v[48:51]
	v_mfma_f32_16x16x32_bf16 v[126:129], v[126:129], v[32:35], v[52:55]
	v_mfma_f32_16x16x32_bf16 v[172:175], v[172:175], v[32:35], v[56:59]
	v_mfma_f32_16x16x32_bf16 v[176:179], v[176:179], v[32:35], v[60:63]
	ds_read_b128 v[32:35], v87 offset:32768
	s_waitcnt lgkmcnt(0)
	v_mfma_f32_16x16x32_bf16 v[56:59], v[192:195], v[32:35], v[0:3]
	s_nop 2
	ds_read_b128 v[0:3], v141 offset:49664
	s_waitcnt lgkmcnt(0)
	v_mfma_f32_16x16x32_bf16 v[60:63], v[0:3], v[32:35], v[4:7]
	s_nop 2
	ds_read_b128 v[4:7], v141 offset:53248
	s_waitcnt lgkmcnt(0)
	v_mfma_f32_16x16x32_bf16 v[48:51], v[4:7], v[32:35], v[8:11]
	s_nop 2
	ds_read_b128 v[8:11], v87 offset:34816
	v_mfma_f32_16x16x32_bf16 v[52:55], v[196:199], v[32:35], v[12:15]
	s_waitcnt lgkmcnt(0)
	v_mfma_f32_16x16x32_bf16 v[44:47], v[192:195], v[8:11], v[16:19]
	v_mfma_f32_16x16x32_bf16 v[40:43], v[0:3], v[8:11], v[20:23]
	v_mfma_f32_16x16x32_bf16 v[36:39], v[4:7], v[8:11], v[24:27]
	v_mfma_f32_16x16x32_bf16 v[32:35], v[196:199], v[8:11], v[28:31]
	ds_read_b128 v[8:11], v87 offset:36864
	s_waitcnt lgkmcnt(0)
	v_mfma_f32_16x16x32_bf16 v[16:19], v[196:199], v[8:11], v[122:125]
	s_nop 2
	ds_read_b128 v[122:125], v87 offset:38912
	s_waitcnt vmcnt(0)
	v_mfma_f32_16x16x32_bf16 v[28:31], v[192:195], v[8:11], v[180:183]
	s_waitcnt lgkmcnt(0)
	s_barrier
	v_mfma_f32_16x16x32_bf16 v[24:27], v[0:3], v[8:11], v[184:187]
	v_mfma_f32_16x16x32_bf16 v[20:23], v[4:7], v[8:11], v[188:191]
	v_mfma_f32_16x16x32_bf16 v[8:11], v[192:195], v[122:125], v[118:121]
	v_mfma_f32_16x16x32_bf16 v[12:15], v[0:3], v[122:125], v[126:129]
	v_mfma_f32_16x16x32_bf16 v[0:3], v[4:7], v[122:125], v[172:175]
	v_mfma_f32_16x16x32_bf16 v[4:7], v[196:199], v[122:125], v[176:179]
	s_cbranch_scc0 .LBB0_557
	s_ashr_i32 s8, s16, 31
	s_lshr_b32 s8, s8, 27
	s_add_i32 s9, s16, s8
	s_lshl_b32 s8, s9, 2
	s_and_b32 s9, s9, 0x1ffffe0
	s_and_b32 s8, s8, 0xffffff80
	s_sub_i32 s9, s16, s9
	s_lshl_b32 s10, s9, 7
	s_ashr_i32 s9, s8, 31
	s_lshl_b64 s[8:9], s[8:9], 11
	v_readlane_b32 s11, v245, 53
	s_add_u32 s8, s11, s8
	v_readlane_b32 s11, v245, 54
	s_addc_u32 s9, s11, s9
	s_ashr_i32 s11, s10, 31
	s_lshl_b64 s[10:11], s[10:11], 11
	s_add_u32 s10, s14, s10
	v_readfirstlane_b32 s12, v149
	s_addc_u32 s11, s15, s11
	s_mov_b32 m0, s12
	v_readfirstlane_b32 s12, v143
	global_load_lds_dwordx4 v168, s[8:9]
	v_lshl_add_u64 v[110:111], v[64:65], 1, s[10:11]
	s_mov_b32 m0, s12
	v_readfirstlane_b32 s12, v144
	global_load_lds_dwordx4 v[110:111], off
	s_mov_b32 m0, s12
	v_readfirstlane_b32 s12, v145
	global_load_lds_dwordx4 v169, s[8:9]
	v_lshl_add_u64 v[110:111], v[66:67], 1, s[10:11]
	s_mov_b32 m0, s12
	v_readfirstlane_b32 s12, v162
	global_load_lds_dwordx4 v[110:111], off
	s_mov_b32 m0, s12
	v_readfirstlane_b32 s12, v163
	global_load_lds_dwordx4 v170, s[8:9]
	v_lshl_add_u64 v[110:111], v[68:69], 1, s[10:11]
	s_mov_b32 m0, s12
	v_readfirstlane_b32 s12, v164
	global_load_lds_dwordx4 v[110:111], off
	s_mov_b32 m0, s12
	v_lshl_add_u64 v[110:111], v[70:71], 1, s[10:11]
	global_load_lds_dwordx4 v171, s[8:9]
	v_readfirstlane_b32 s8, v165
	s_mov_b32 m0, s8
	s_nop 0
	global_load_lds_dwordx4 v[110:111], off
	s_branch .LBB0_557

; __device__ __forceinline__ f32x4 mfma16(bf16x8 a, bf16x8 b, f32x4 c) { return __builtin_amdgcn_mfma_f32_16x16x32_bf16(a, b, c, 0, 0, 0); }
; template <class Epi>
; __device__ __forceinline__ void gemm_tile(const bf16_t* __restrict__ A, const bf16_t* __restrict__ Bt, int K, int row0, int col0, const Epi& epi, char* smem,
;                                           bool prefetched, bool nvalid, int nrow0, int ncol0) {
;     ...
;     for (int kt = 0; kt < nk; ++kt) {
;         const int cur = kt & 1;
;         if (kt + 1 < nk) GLDS_STAGE(cur ^ 1, pA, pB, kt + 1);
;         const char* cb = smem + cur * 2 * TILE_B;
; #pragma unroll
;         for (int ks = 0; ks < 2; ++ks) {
;             bf16x8 a[4], b[4];
; #pragma unroll
;             for (int m = 0; m < 4; ++m) a[m] = *(const bf16x8*)(cb + offA[m][ks]);
; #pragma unroll
;             for (int n = 0; n < 4; ++n) b[n] = *(const bf16x8*)(cb + offB[n][ks]);
; #pragma unroll
;             for (int m = 0; m < 4; ++m)
; #pragma unroll
;                 for (int n = 0; n < 4; ++n) acc[m][n] = mfma16(b[n], a[m], acc[m][n]);
;         }
;         asm volatile("s_waitcnt vmcnt(0)" ::: "memory");
;         __syncthreads();
;     }
.LBB0_619:
	s_and_b32 s3, s1, 0x8000
	s_xor_b32 s8, s3, 0x8000
	v_add_u32_e32 v141, s8, v149
	v_add_u32_e32 v172, 0x4000, v141
	v_readfirstlane_b32 s8, v141
	v_lshl_add_u64 v[130:131], v[92:93], 0, s[6:7]
	v_add_u32_e32 v173, 0x1000, v141
	v_readfirstlane_b32 s9, v172
	s_mov_b32 m0, s8
	v_lshl_add_u64 v[142:143], v[100:101], 0, s[6:7]
	v_add_u32_e32 v174, 0x5000, v141
	v_readfirstlane_b32 s10, v173
	global_load_lds_dwordx4 v[130:131], off
	s_mov_b32 m0, s9
	v_lshl_add_u64 v[144:145], v[94:95], 0, s[6:7]
	v_add_u32_e32 v175, 0x2000, v141
	v_readfirstlane_b32 s11, v174
	global_load_lds_dwordx4 v[142:143], off
	s_mov_b32 m0, s10
	v_lshl_add_u64 v[162:163], v[102:103], 0, s[6:7]
	v_add_u32_e32 v176, 0x6000, v141
	v_readfirstlane_b32 s12, v175
	global_load_lds_dwordx4 v[144:145], off
	s_mov_b32 m0, s11
	v_lshl_add_u64 v[164:165], v[96:97], 0, s[6:7]
	v_add_u32_e32 v177, 0x3000, v141
	v_readfirstlane_b32 s13, v176
	global_load_lds_dwordx4 v[162:163], off
	s_mov_b32 m0, s12
	v_lshl_add_u64 v[166:167], v[104:105], 0, s[6:7]
	v_add_u32_e32 v141, 0x7000, v141
	v_readfirstlane_b32 s17, v177
	global_load_lds_dwordx4 v[164:165], off
	s_mov_b32 m0, s13
	v_lshl_add_u64 v[168:169], v[98:99], 0, s[6:7]
	v_readfirstlane_b32 s18, v141
	global_load_lds_dwordx4 v[166:167], off
	s_mov_b32 m0, s17
	v_lshl_add_u64 v[170:171], v[106:107], 0, s[6:7]
	global_load_lds_dwordx4 v[168:169], off
	s_mov_b32 m0, s18
	v_or_b32_e32 v137, s3, v110
	global_load_lds_dwordx4 v[170:171], off
	v_add_u32_e32 v129, s3, v108
	ds_read_b128 v[142:145], v137 offset:16384
	ds_read_b128 v[162:165], v137 offset:16896
	ds_read_b128 v[166:169], v129
	ds_read_b128 v[170:173], v129 offset:2048
	ds_read_b128 v[174:177], v137 offset:20480
	ds_read_b128 v[178:181], v137 offset:20992
	s_waitcnt lgkmcnt(0)
	v_mfma_f32_16x16x32_bf16 v[0:3], v[142:145], v[166:169], v[0:3]
	v_or_b32_e32 v130, s3, v111
	s_add_u32 s6, s6, 0x80
	s_addc_u32 s7, s7, 0
	v_mfma_f32_16x16x32_bf16 v[4:7], v[162:165], v[166:169], v[4:7]
	s_add_i32 s1, s1, 0x8000
	s_cmpk_eq_i32 s6, 0x1f80
	v_mfma_f32_16x16x32_bf16 v[8:11], v[174:177], v[166:169], v[8:11]
	v_mfma_f32_16x16x32_bf16 v[12:15], v[178:181], v[166:169], v[12:15]
	v_mfma_f32_16x16x32_bf16 v[16:19], v[142:145], v[170:173], v[16:19]
	v_mfma_f32_16x16x32_bf16 v[20:23], v[162:165], v[170:173], v[20:23]
	v_mfma_f32_16x16x32_bf16 v[24:27], v[174:177], v[170:173], v[24:27]
	v_mfma_f32_16x16x32_bf16 v[28:31], v[178:181], v[170:173], v[28:31]
	ds_read_b128 v[166:169], v129 offset:4096
	ds_read_b128 v[170:173], v129 offset:6144
	v_add_u32_e32 v129, s3, v109
	s_waitcnt lgkmcnt(1)
	v_mfma_f32_16x16x32_bf16 v[32:35], v[142:145], v[166:169], v[32:35]
	v_mfma_f32_16x16x32_bf16 v[36:39], v[162:165], v[166:169], v[36:39]
	v_mfma_f32_16x16x32_bf16 v[40:43], v[174:177], v[166:169], v[40:43]
	v_mfma_f32_16x16x32_bf16 v[44:47], v[178:181], v[166:169], v[44:47]
	s_waitcnt lgkmcnt(0)
	v_mfma_f32_16x16x32_bf16 v[48:51], v[142:145], v[170:173], v[48:51]
	v_mfma_f32_16x16x32_bf16 v[52:55], v[162:165], v[170:173], v[52:55]
	ds_read_b128 v[142:145], v130 offset:16384
	ds_read_b128 v[162:165], v130 offset:16896
	v_mfma_f32_16x16x32_bf16 v[56:59], v[174:177], v[170:173], v[56:59]
	v_mfma_f32_16x16x32_bf16 v[60:63], v[178:181], v[170:173], v[60:63]
	ds_read_b128 v[166:169], v129
	ds_read_b128 v[170:173], v129 offset:2048
	ds_read_b128 v[174:177], v130 offset:20480
	ds_read_b128 v[178:181], v130 offset:20992
	s_waitcnt lgkmcnt(3)
	v_mfma_f32_16x16x32_bf16 v[0:3], v[142:145], v[166:169], v[0:3]
	v_mfma_f32_16x16x32_bf16 v[4:7], v[162:165], v[166:169], v[4:7]
	s_waitcnt lgkmcnt(1)
	v_mfma_f32_16x16x32_bf16 v[8:11], v[174:177], v[166:169], v[8:11]
	s_waitcnt lgkmcnt(0)
	v_mfma_f32_16x16x32_bf16 v[12:15], v[178:181], v[166:169], v[12:15]
	v_mfma_f32_16x16x32_bf16 v[16:19], v[142:145], v[170:173], v[16:19]
	v_mfma_f32_16x16x32_bf16 v[20:23], v[162:165], v[170:173], v[20:23]
	v_mfma_f32_16x16x32_bf16 v[24:27], v[174:177], v[170:173], v[24:27]
	v_mfma_f32_16x16x32_bf16 v[28:31], v[178:181], v[170:173], v[28:31]
	ds_read_b128 v[166:169], v129 offset:4096
	ds_read_b128 v[170:173], v129 offset:6144
	s_waitcnt vmcnt(0)
	s_waitcnt lgkmcnt(0)
	v_mfma_f32_16x16x32_bf16 v[32:35], v[142:145], v[166:169], v[32:35]
	s_barrier
	v_mfma_f32_16x16x32_bf16 v[36:39], v[162:165], v[166:169], v[36:39]
	v_mfma_f32_16x16x32_bf16 v[40:43], v[174:177], v[166:169], v[40:43]
	v_mfma_f32_16x16x32_bf16 v[44:47], v[178:181], v[166:169], v[44:47]
	v_mfma_f32_16x16x32_bf16 v[48:51], v[142:145], v[170:173], v[48:51]
	v_mfma_f32_16x16x32_bf16 v[52:55], v[162:165], v[170:173], v[52:55]
	v_mfma_f32_16x16x32_bf16 v[56:59], v[174:177], v[170:173], v[56:59]
	v_mfma_f32_16x16x32_bf16 v[60:63], v[178:181], v[170:173], v[60:63]
	s_cbranch_scc0 .LBB0_619
; __device__ __forceinline__ f32x4 mfma16(bf16x8 a, bf16x8 b, f32x4 c) { return __builtin_amdgcn_mfma_f32_16x16x32_bf16(a, b, c, 0, 0, 0); }
; template <class Epi>
; __device__ __forceinline__ void gemm_tile(const bf16_t* __restrict__ A, const bf16_t* __restrict__ Bt, int K, int row0, int col0, const Epi& epi, char* smem,
;                                           bool prefetched, bool nvalid, int nrow0, int ncol0) {
;     ...
;         const char* cb = smem + cur * 2 * TILE_B;
; #pragma unroll
;         for (int ks = 0; ks < 2; ++ks) {
;             bf16x8 a[4], b[4];
; #pragma unroll
;             for (int m = 0; m < 4; ++m) a[m] = *(const bf16x8*)(cb + offA[m][ks]);
; #pragma unroll
;             for (int n = 0; n < 4; ++n) b[n] = *(const bf16x8*)(cb + offB[n][ks]);
; #pragma unroll
;             for (int m = 0; m < 4; ++m)
; #pragma unroll
;                 for (int n = 0; n < 4; ++n) acc[m][n] = mfma16(b[n], a[m], acc[m][n]);
;         }
;         asm volatile("s_waitcnt vmcnt(0)" ::: "memory");
;         __syncthreads();
;     }
;     if (nvalid) { const bf16_t* qA = A + (size_t)nrow0 * K; const bf16_t* qB = Bt + (size_t)ncol0 * K; GLDS_STAGE(0, qA, qB, 0); }
; template <class Epi>
; __device__ __forceinline__ void gemm_phase(const bf16_t* A, const bf16_t* Bt, int M, int N, int K, const Epi& epi, char* smem) {
;     ...
;     for (int i = blockIdx.x; i < ntiles; i += G) {
;         const int j = i + G; const bool nv = j < ntiles;
;         gemm_tile(A, Bt, K, (i / nN) << 7, (i % nN) << 7, epi, smem, pre, nv, (j / nN) << 7, (j % nN) << 7);
	ds_read_b128 v[92:95], v110 offset:49152
	ds_read_b128 v[96:99], v110 offset:49664
	ds_read_b128 v[100:103], v108 offset:32768
	ds_read_b128 v[104:107], v108 offset:34816
	ds_read_b128 v[142:145], v110 offset:53248
	ds_read_b128 v[162:165], v110 offset:53760
	s_add_i32 s16, s16, s58
	s_waitcnt lgkmcnt(3)
	v_mfma_f32_16x16x32_bf16 v[0:3], v[92:95], v[100:103], v[0:3]
	s_cmpk_gt_i32 s16, 0x7ff
	s_cselect_b64 s[6:7], -1, 0
	s_cmpk_lt_i32 s16, 0x800
	v_mfma_f32_16x16x32_bf16 v[4:7], v[96:99], v[100:103], v[4:7]
	s_waitcnt lgkmcnt(1)
	v_mfma_f32_16x16x32_bf16 v[8:11], v[142:145], v[100:103], v[8:11]
	s_waitcnt lgkmcnt(0)
	v_mfma_f32_16x16x32_bf16 v[12:15], v[162:165], v[100:103], v[12:15]
	v_mfma_f32_16x16x32_bf16 v[16:19], v[92:95], v[104:107], v[16:19]
	v_mfma_f32_16x16x32_bf16 v[20:23], v[96:99], v[104:107], v[20:23]
	v_mfma_f32_16x16x32_bf16 v[24:27], v[142:145], v[104:107], v[24:27]
	v_mfma_f32_16x16x32_bf16 v[28:31], v[162:165], v[104:107], v[28:31]
	ds_read_b128 v[100:103], v108 offset:36864
	ds_read_b128 v[104:107], v108 offset:38912
	ds_read_b128 v[178:181], v111 offset:49152
	s_waitcnt lgkmcnt(2)
	v_mfma_f32_16x16x32_bf16 v[166:169], v[92:95], v[100:103], v[32:35]
	v_mfma_f32_16x16x32_bf16 v[170:173], v[96:99], v[100:103], v[36:39]
	v_mfma_f32_16x16x32_bf16 v[174:177], v[142:145], v[100:103], v[40:43]
	v_mfma_f32_16x16x32_bf16 v[100:103], v[162:165], v[100:103], v[44:47]
	s_waitcnt lgkmcnt(1)
	v_mfma_f32_16x16x32_bf16 v[92:95], v[92:95], v[104:107], v[48:51]
	v_mfma_f32_16x16x32_bf16 v[96:99], v[96:99], v[104:107], v[52:55]
	v_mfma_f32_16x16x32_bf16 v[142:145], v[142:145], v[104:107], v[56:59]
	v_mfma_f32_16x16x32_bf16 v[104:107], v[162:165], v[104:107], v[60:63]
	ds_read_b128 v[162:165], v111 offset:49664
	ds_read_b128 v[32:35], v109 offset:32768
	ds_read_b128 v[36:39], v109 offset:34816
	ds_read_b128 v[182:185], v111 offset:53760
	s_waitcnt lgkmcnt(2)
	v_mfma_f32_16x16x32_bf16 v[52:55], v[178:181], v[32:35], v[0:3]
	s_nop 2
	ds_read_b128 v[0:3], v111 offset:53248
	v_mfma_f32_16x16x32_bf16 v[56:59], v[162:165], v[32:35], v[4:7]
	s_nop 2
	ds_read_b128 v[4:7], v109 offset:36864
	ds_read_b128 v[186:189], v109 offset:38912
	s_waitcnt vmcnt(0)
	s_waitcnt lgkmcnt(0)
	v_mfma_f32_16x16x32_bf16 v[60:63], v[0:3], v[32:35], v[8:11]
	s_barrier
	v_mfma_f32_16x16x32_bf16 v[48:51], v[182:185], v[32:35], v[12:15]
	v_mfma_f32_16x16x32_bf16 v[44:47], v[178:181], v[36:39], v[16:19]
	v_mfma_f32_16x16x32_bf16 v[40:43], v[162:165], v[36:39], v[20:23]
	v_mfma_f32_16x16x32_bf16 v[32:35], v[0:3], v[36:39], v[24:27]
	v_mfma_f32_16x16x32_bf16 v[24:27], v[182:185], v[36:39], v[28:31]
	v_mfma_f32_16x16x32_bf16 v[36:39], v[178:181], v[4:7], v[166:169]
	v_mfma_f32_16x16x32_bf16 v[28:31], v[162:165], v[4:7], v[170:173]
	v_mfma_f32_16x16x32_bf16 v[20:23], v[0:3], v[4:7], v[174:177]
	v_mfma_f32_16x16x32_bf16 v[16:19], v[182:185], v[4:7], v[100:103]
	v_mfma_f32_16x16x32_bf16 v[12:15], v[178:181], v[186:189], v[92:95]
	v_mfma_f32_16x16x32_bf16 v[8:11], v[162:165], v[186:189], v[96:99]
	v_mfma_f32_16x16x32_bf16 v[4:7], v[0:3], v[186:189], v[142:145]
	v_mfma_f32_16x16x32_bf16 v[0:3], v[182:185], v[186:189], v[104:107]
	s_cbranch_scc0 .LBB0_613
	s_ashr_i32 s1, s16, 31
	s_lshr_b32 s1, s1, 29
	s_add_i32 s1, s16, s1
	s_lshl_b32 s3, s1, 4
	s_and_b32 s8, s3, 0xffffff80
	s_and_b32 s1, s1, 0x1fffff8
	s_sub_i32 s1, s16, s1
	s_ashr_i32 s9, s8, 31
	s_lshl_b32 s10, s1, 7
	s_lshl_b64 s[8:9], s[8:9], 13
	v_readlane_b32 s12, v245, 55
	v_readlane_b32 s13, v245, 56
	s_add_u32 s8, s12, s8
	s_addc_u32 s9, s13, s9
	s_ashr_i32 s11, s10, 31
	s_lshl_b64 s[10:11], s[10:11], 13
	s_add_u32 s10, s14, s10
	v_readfirstlane_b32 s1, v149
	s_addc_u32 s11, s15, s11
	s_mov_b32 m0, s1
	v_readfirstlane_b32 s1, v118
	global_load_lds_dwordx4 v125, s[8:9]
	v_lshl_add_u64 v[92:93], v[64:65], 1, s[10:11]
	s_mov_b32 m0, s1
	v_readfirstlane_b32 s1, v119
	global_load_lds_dwordx4 v[92:93], off
	s_mov_b32 m0, s1
	v_readfirstlane_b32 s1, v120
	global_load_lds_dwordx4 v126, s[8:9]
	v_lshl_add_u64 v[92:93], v[66:67], 1, s[10:11]
	s_mov_b32 m0, s1
	v_readfirstlane_b32 s1, v121
	global_load_lds_dwordx4 v[92:93], off
	s_mov_b32 m0, s1
	v_readfirstlane_b32 s1, v122
	global_load_lds_dwordx4 v127, s[8:9]
	v_lshl_add_u64 v[92:93], v[68:69], 1, s[10:11]
	s_mov_b32 m0, s1
	v_readfirstlane_b32 s1, v123
	global_load_lds_dwordx4 v[92:93], off
	s_mov_b32 m0, s1
	v_readfirstlane_b32 s1, v124
	global_load_lds_dwordx4 v128, s[8:9]
	v_lshl_add_u64 v[92:93], v[70:71], 1, s[10:11]
	s_mov_b32 m0, s1
	s_nop 0
	global_load_lds_dwordx4 v[92:93], off
	s_branch .LBB0_613

; __device__ __forceinline__ f32x4 mfma16(bf16x8 a, bf16x8 b, f32x4 c) { return __builtin_amdgcn_mfma_f32_16x16x32_bf16(a, b, c, 0, 0, 0); }
; template <class Epi>
; __device__ __forceinline__ void gemm_tile(const bf16_t* __restrict__ A, const bf16_t* __restrict__ Bt, int K, int row0, int col0, const Epi& epi, char* smem,
;                                           bool prefetched, bool nvalid, int nrow0, int ncol0) {
;     ...
;     for (int kt = 0; kt < nk; ++kt) {
;         const int cur = kt & 1;
;         if (kt + 1 < nk) GLDS_STAGE(cur ^ 1, pA, pB, kt + 1);
;         const char* cb = smem + cur * 2 * TILE_B;
; #pragma unroll
;         for (int ks = 0; ks < 2; ++ks) {
;             bf16x8 a[4], b[4];
; #pragma unroll
;             for (int m = 0; m < 4; ++m) a[m] = *(const bf16x8*)(cb + offA[m][ks]);
; #pragma unroll
;             for (int n = 0; n < 4; ++n) b[n] = *(const bf16x8*)(cb + offB[n][ks]);
; #pragma unroll
;             for (int m = 0; m < 4; ++m)
; #pragma unroll
;                 for (int n = 0; n < 4; ++n) acc[m][n] = mfma16(b[n], a[m], acc[m][n]);
;         }
;         asm volatile("s_waitcnt vmcnt(0)" ::: "memory");
;         __syncthreads();
;     }
.LBB0_723:
	s_and_b32 s10, s7, 0x8000
	s_xor_b32 s11, s10, 0x8000
	v_add_u32_e32 v188, s11, v149
	v_add_u32_e32 v189, 0x4000, v188
	v_readfirstlane_b32 s11, v188
	v_lshl_add_u64 v[80:81], v[64:65], 0, s[0:1]
	v_add_u32_e32 v190, 0x1000, v188
	v_readfirstlane_b32 s12, v189
	s_mov_b32 m0, s11
	v_lshl_add_u64 v[82:83], v[72:73], 0, s[0:1]
	v_add_u32_e32 v191, 0x5000, v188
	v_readfirstlane_b32 s13, v190
	global_load_lds_dwordx4 v[80:81], off
	s_mov_b32 m0, s12
	v_lshl_add_u64 v[128:129], v[66:67], 0, s[0:1]
	v_add_u32_e32 v193, 0x2000, v188
	v_readfirstlane_b32 s14, v191
	global_load_lds_dwordx4 v[82:83], off
	s_mov_b32 m0, s13
	v_lshl_add_u64 v[130:131], v[74:75], 0, s[0:1]
	v_add_u32_e32 v194, 0x6000, v188
	v_readfirstlane_b32 s15, v193
	global_load_lds_dwordx4 v[128:129], off
	s_mov_b32 m0, s14
	v_lshl_add_u64 v[180:181], v[68:69], 0, s[0:1]
	v_add_u32_e32 v195, 0x3000, v188
	v_readfirstlane_b32 s16, v194
	global_load_lds_dwordx4 v[130:131], off
	s_mov_b32 m0, s15
	v_lshl_add_u64 v[182:183], v[76:77], 0, s[0:1]
	v_add_u32_e32 v188, 0x7000, v188
	v_readfirstlane_b32 s17, v195
	global_load_lds_dwordx4 v[180:181], off
	s_mov_b32 m0, s16
	v_lshl_add_u64 v[184:185], v[70:71], 0, s[0:1]
	v_readfirstlane_b32 s18, v188
	global_load_lds_dwordx4 v[182:183], off
	s_mov_b32 m0, s17
	v_lshl_add_u64 v[186:187], v[78:79], 0, s[0:1]
	global_load_lds_dwordx4 v[184:185], off
	s_mov_b32 m0, s18
	v_or_b32_e32 v192, s10, v143
	global_load_lds_dwordx4 v[186:187], off
	v_add_u32_e32 v179, s10, v137
	ds_read_b128 v[80:83], v192 offset:16384
	ds_read_b128 v[128:131], v192 offset:16896
	ds_read_b128 v[180:183], v179
	ds_read_b128 v[184:187], v179 offset:2048
	ds_read_b128 v[188:191], v192 offset:20480
	ds_read_b128 v[192:195], v192 offset:20992
	s_waitcnt lgkmcnt(0)
	v_mfma_f32_16x16x32_bf16 v[0:3], v[80:83], v[180:183], v[0:3]
	v_or_b32_e32 v196, s10, v142
	s_add_i32 s7, s7, 0x8000
	s_add_u32 s0, s0, 0x80
	v_mfma_f32_16x16x32_bf16 v[4:7], v[128:131], v[180:183], v[4:7]
	s_addc_u32 s1, s1, 0
	s_cmpk_eq_i32 s0, 0x780
	v_mfma_f32_16x16x32_bf16 v[8:11], v[188:191], v[180:183], v[8:11]
	v_mfma_f32_16x16x32_bf16 v[12:15], v[192:195], v[180:183], v[12:15]
	v_mfma_f32_16x16x32_bf16 v[16:19], v[80:83], v[184:187], v[16:19]
	v_mfma_f32_16x16x32_bf16 v[20:23], v[128:131], v[184:187], v[20:23]
	v_mfma_f32_16x16x32_bf16 v[24:27], v[188:191], v[184:187], v[24:27]
	v_mfma_f32_16x16x32_bf16 v[28:31], v[192:195], v[184:187], v[28:31]
	ds_read_b128 v[180:183], v179 offset:4096
	ds_read_b128 v[184:187], v179 offset:6144
	v_add_u32_e32 v179, s10, v141
	s_waitcnt lgkmcnt(1)
	v_mfma_f32_16x16x32_bf16 v[32:35], v[80:83], v[180:183], v[32:35]
	v_mfma_f32_16x16x32_bf16 v[36:39], v[128:131], v[180:183], v[36:39]
	v_mfma_f32_16x16x32_bf16 v[40:43], v[188:191], v[180:183], v[40:43]
	v_mfma_f32_16x16x32_bf16 v[44:47], v[192:195], v[180:183], v[44:47]
	s_waitcnt lgkmcnt(0)
	v_mfma_f32_16x16x32_bf16 v[48:51], v[80:83], v[184:187], v[48:51]
	v_mfma_f32_16x16x32_bf16 v[52:55], v[128:131], v[184:187], v[52:55]
	ds_read_b128 v[80:83], v196 offset:16384
	ds_read_b128 v[128:131], v196 offset:16896
	v_mfma_f32_16x16x32_bf16 v[56:59], v[188:191], v[184:187], v[56:59]
	v_mfma_f32_16x16x32_bf16 v[60:63], v[192:195], v[184:187], v[60:63]
	ds_read_b128 v[180:183], v179
	ds_read_b128 v[184:187], v179 offset:2048
	ds_read_b128 v[188:191], v196 offset:20480
	ds_read_b128 v[192:195], v196 offset:20992
	s_waitcnt lgkmcnt(3)
	v_mfma_f32_16x16x32_bf16 v[0:3], v[80:83], v[180:183], v[0:3]
	v_mfma_f32_16x16x32_bf16 v[4:7], v[128:131], v[180:183], v[4:7]
	s_waitcnt lgkmcnt(1)
	v_mfma_f32_16x16x32_bf16 v[8:11], v[188:191], v[180:183], v[8:11]
	s_waitcnt lgkmcnt(0)
	v_mfma_f32_16x16x32_bf16 v[12:15], v[192:195], v[180:183], v[12:15]
	v_mfma_f32_16x16x32_bf16 v[16:19], v[80:83], v[184:187], v[16:19]
	v_mfma_f32_16x16x32_bf16 v[20:23], v[128:131], v[184:187], v[20:23]
	v_mfma_f32_16x16x32_bf16 v[24:27], v[188:191], v[184:187], v[24:27]
	v_mfma_f32_16x16x32_bf16 v[28:31], v[192:195], v[184:187], v[28:31]
	ds_read_b128 v[180:183], v179 offset:4096
	ds_read_b128 v[184:187], v179 offset:6144
	s_waitcnt vmcnt(0)
	s_waitcnt lgkmcnt(0)
	v_mfma_f32_16x16x32_bf16 v[32:35], v[80:83], v[180:183], v[32:35]
	s_barrier
	v_mfma_f32_16x16x32_bf16 v[36:39], v[128:131], v[180:183], v[36:39]
	v_mfma_f32_16x16x32_bf16 v[40:43], v[188:191], v[180:183], v[40:43]
	v_mfma_f32_16x16x32_bf16 v[44:47], v[192:195], v[180:183], v[44:47]
	v_mfma_f32_16x16x32_bf16 v[48:51], v[80:83], v[184:187], v[48:51]
	v_mfma_f32_16x16x32_bf16 v[52:55], v[128:131], v[184:187], v[52:55]
	v_mfma_f32_16x16x32_bf16 v[56:59], v[188:191], v[184:187], v[56:59]
	v_mfma_f32_16x16x32_bf16 v[60:63], v[192:195], v[184:187], v[60:63]
	s_cbranch_scc0 .LBB0_723
; __device__ __forceinline__ f32x4 mfma16(bf16x8 a, bf16x8 b, f32x4 c) { return __builtin_amdgcn_mfma_f32_16x16x32_bf16(a, b, c, 0, 0, 0); }
; template <class Epi>
; __device__ __forceinline__ void gemm_tile(const bf16_t* __restrict__ A, const bf16_t* __restrict__ Bt, int K, int row0, int col0, const Epi& epi, char* smem,
;                                           bool prefetched, bool nvalid, int nrow0, int ncol0) {
;     ...
;         const char* cb = smem + cur * 2 * TILE_B;
; #pragma unroll
;         for (int ks = 0; ks < 2; ++ks) {
;             bf16x8 a[4], b[4];
; #pragma unroll
;             for (int m = 0; m < 4; ++m) a[m] = *(const bf16x8*)(cb + offA[m][ks]);
; #pragma unroll
;             for (int n = 0; n < 4; ++n) b[n] = *(const bf16x8*)(cb + offB[n][ks]);
; #pragma unroll
;             for (int m = 0; m < 4; ++m)
; #pragma unroll
;                 for (int n = 0; n < 4; ++n) acc[m][n] = mfma16(b[n], a[m], acc[m][n]);
;         }
;         asm volatile("s_waitcnt vmcnt(0)" ::: "memory");
;         __syncthreads();
;     }
;     if (nvalid) { const bf16_t* qA = A + (size_t)nrow0 * K; const bf16_t* qB = Bt + (size_t)ncol0 * K; GLDS_STAGE(0, qA, qB, 0); }
; template <class Epi>
; __device__ __forceinline__ void gemm_phase(const bf16_t* A, const bf16_t* Bt, int M, int N, int K, const Epi& epi, char* smem) {
;     ...
;     for (int i = blockIdx.x; i < ntiles; i += G) {
;         const int j = i + G; const bool nv = j < ntiles;
;         gemm_tile(A, Bt, K, (i / nN) << 7, (i % nN) << 7, epi, smem, pre, nv, (j / nN) << 7, (j % nN) << 7);
	ds_read_b128 v[64:67], v143 offset:49152
	ds_read_b128 v[68:71], v137 offset:32768
	ds_read_b128 v[72:75], v143 offset:49664
	ds_read_b128 v[76:79], v143 offset:53248
	ds_read_b128 v[80:83], v143 offset:53760
	s_add_i32 s24, s24, s58
	s_waitcnt lgkmcnt(3)
	v_mfma_f32_16x16x32_bf16 v[0:3], v[64:67], v[68:71], v[0:3]
	s_cmpk_gt_i32 s24, 0xfff
	s_cselect_b64 s[10:11], -1, 0
	s_cmpk_lt_i32 s24, 0x1000
	s_waitcnt lgkmcnt(2)
	v_mfma_f32_16x16x32_bf16 v[4:7], v[72:75], v[68:71], v[4:7]
	ds_read_b128 v[188:191], v142 offset:49152
	ds_read_b128 v[192:195], v142 offset:53760
	s_waitcnt lgkmcnt(3)
	v_mfma_f32_16x16x32_bf16 v[8:11], v[76:79], v[68:71], v[8:11]
	s_waitcnt lgkmcnt(2)
	v_mfma_f32_16x16x32_bf16 v[12:15], v[80:83], v[68:71], v[12:15]
	ds_read_b128 v[68:71], v137 offset:34816
	s_waitcnt lgkmcnt(0)
	v_mfma_f32_16x16x32_bf16 v[16:19], v[64:67], v[68:71], v[16:19]
	v_mfma_f32_16x16x32_bf16 v[20:23], v[72:75], v[68:71], v[20:23]
	v_mfma_f32_16x16x32_bf16 v[24:27], v[76:79], v[68:71], v[24:27]
	v_mfma_f32_16x16x32_bf16 v[28:31], v[80:83], v[68:71], v[28:31]
	ds_read_b128 v[68:71], v137 offset:36864
	s_waitcnt lgkmcnt(0)
	v_mfma_f32_16x16x32_bf16 v[128:131], v[64:67], v[68:71], v[32:35]
	s_nop 2
	ds_read_b128 v[32:35], v137 offset:38912
	v_mfma_f32_16x16x32_bf16 v[180:183], v[72:75], v[68:71], v[36:39]
	v_mfma_f32_16x16x32_bf16 v[184:187], v[76:79], v[68:71], v[40:43]
	v_mfma_f32_16x16x32_bf16 v[68:71], v[80:83], v[68:71], v[44:47]
	s_waitcnt lgkmcnt(0)
	v_mfma_f32_16x16x32_bf16 v[64:67], v[64:67], v[32:35], v[48:51]
	v_mfma_f32_16x16x32_bf16 v[72:75], v[72:75], v[32:35], v[52:55]
	v_mfma_f32_16x16x32_bf16 v[76:79], v[76:79], v[32:35], v[56:59]
	v_mfma_f32_16x16x32_bf16 v[80:83], v[80:83], v[32:35], v[60:63]
	ds_read_b128 v[32:35], v141 offset:32768
	s_waitcnt lgkmcnt(0)
	v_mfma_f32_16x16x32_bf16 v[56:59], v[188:191], v[32:35], v[0:3]
	s_nop 2
	ds_read_b128 v[0:3], v142 offset:49664
	s_waitcnt lgkmcnt(0)
	v_mfma_f32_16x16x32_bf16 v[60:63], v[0:3], v[32:35], v[4:7]
	s_nop 2
	ds_read_b128 v[4:7], v142 offset:53248
	s_waitcnt lgkmcnt(0)
	v_mfma_f32_16x16x32_bf16 v[48:51], v[4:7], v[32:35], v[8:11]
	s_nop 2
	ds_read_b128 v[8:11], v141 offset:34816
	v_mfma_f32_16x16x32_bf16 v[52:55], v[192:195], v[32:35], v[12:15]
	s_waitcnt lgkmcnt(0)
	v_mfma_f32_16x16x32_bf16 v[40:43], v[188:191], v[8:11], v[16:19]
	v_mfma_f32_16x16x32_bf16 v[44:47], v[0:3], v[8:11], v[20:23]
	v_mfma_f32_16x16x32_bf16 v[32:35], v[4:7], v[8:11], v[24:27]
	v_mfma_f32_16x16x32_bf16 v[36:39], v[192:195], v[8:11], v[28:31]
	ds_read_b128 v[8:11], v141 offset:36864
	s_waitcnt lgkmcnt(0)
	v_mfma_f32_16x16x32_bf16 v[20:23], v[192:195], v[8:11], v[68:71]
	s_nop 2
	ds_read_b128 v[68:71], v141 offset:38912
	s_waitcnt vmcnt(0)
	v_mfma_f32_16x16x32_bf16 v[24:27], v[188:191], v[8:11], v[128:131]
	s_waitcnt lgkmcnt(0)
	s_barrier
	v_mfma_f32_16x16x32_bf16 v[28:31], v[0:3], v[8:11], v[180:183]
	v_mfma_f32_16x16x32_bf16 v[16:19], v[4:7], v[8:11], v[184:187]
	v_mfma_f32_16x16x32_bf16 v[8:11], v[188:191], v[68:71], v[64:67]
	v_mfma_f32_16x16x32_bf16 v[12:15], v[0:3], v[68:71], v[72:75]
	v_mfma_f32_16x16x32_bf16 v[0:3], v[4:7], v[68:71], v[76:79]
	v_mfma_f32_16x16x32_bf16 v[4:7], v[192:195], v[68:71], v[80:83]
	s_cbranch_scc0 .LBB0_726
	s_ashr_i32 s0, s24, 31
	s_lshr_b32 s0, s0, 28
	s_add_i32 s1, s24, s0
	s_lshl_b32 s0, s1, 3
	s_and_b32 s1, s1, 0x1fffff0
	s_and_b32 s0, s0, 0xffffff80
	s_sub_i32 s1, s24, s1
	s_lshl_b32 s12, s1, 7
	s_ashr_i32 s1, s0, 31
	s_lshl_b64 s[0:1], s[0:1], 11
	v_readlane_b32 s7, v245, 53
	s_add_u32 s0, s7, s0
	v_readlane_b32 s7, v245, 54
	s_addc_u32 s1, s7, s1
	s_ashr_i32 s13, s12, 31
	s_lshl_b64 s[12:13], s[12:13], 11
	s_add_u32 s12, s3, s12
	v_readfirstlane_b32 s7, v149
	s_addc_u32 s13, s20, s13
	s_mov_b32 m0, s7
	v_readfirstlane_b32 s7, v163
	global_load_lds_dwordx4 v174, s[0:1]
	v_lshl_add_u64 v[64:65], v[84:85], 1, s[12:13]
	s_mov_b32 m0, s7
	v_readfirstlane_b32 s7, v164
	global_load_lds_dwordx4 v[64:65], off
	s_mov_b32 m0, s7
	v_readfirstlane_b32 s7, v165
	global_load_lds_dwordx4 v175, s[0:1]
	v_lshl_add_u64 v[64:65], v[86:87], 1, s[12:13]
	s_mov_b32 m0, s7
	v_readfirstlane_b32 s7, v166
	global_load_lds_dwordx4 v[64:65], off
	s_mov_b32 m0, s7
	v_readfirstlane_b32 s7, v170
	global_load_lds_dwordx4 v176, s[0:1]
	v_lshl_add_u64 v[64:65], v[88:89], 1, s[12:13]
	s_mov_b32 m0, s7
	v_readfirstlane_b32 s7, v171
	global_load_lds_dwordx4 v[64:65], off
	s_mov_b32 m0, s7
	v_lshl_add_u64 v[64:65], v[90:91], 1, s[12:13]
	global_load_lds_dwordx4 v177, s[0:1]
	v_readfirstlane_b32 s0, v172
	s_mov_b32 m0, s0
	s_nop 0
	global_load_lds_dwordx4 v[64:65], off

; __device__ __forceinline__ f32x4 mfma16(bf16x8 a, bf16x8 b, f32x4 c) { return __builtin_amdgcn_mfma_f32_16x16x32_bf16(a, b, c, 0, 0, 0); }
; template <class Epi>
; __device__ __forceinline__ void gemm_tile(const bf16_t* __restrict__ A, const bf16_t* __restrict__ Bt, int K, int row0, int col0, const Epi& epi, char* smem,
;                                           bool prefetched, bool nvalid, int nrow0, int ncol0) {
;     ...
;     for (int kt = 0; kt < nk; ++kt) {
;         const int cur = kt & 1;
;         if (kt + 1 < nk) GLDS_STAGE(cur ^ 1, pA, pB, kt + 1);
;         const char* cb = smem + cur * 2 * TILE_B;
; #pragma unroll
;         for (int ks = 0; ks < 2; ++ks) {
;             bf16x8 a[4], b[4];
; #pragma unroll
;             for (int m = 0; m < 4; ++m) a[m] = *(const bf16x8*)(cb + offA[m][ks]);
; #pragma unroll
;             for (int n = 0; n < 4; ++n) b[n] = *(const bf16x8*)(cb + offB[n][ks]);
; #pragma unroll
;             for (int m = 0; m < 4; ++m)
; #pragma unroll
;                 for (int n = 0; n < 4; ++n) acc[m][n] = mfma16(b[n], a[m], acc[m][n]);
;         }
;         asm volatile("s_waitcnt vmcnt(0)" ::: "memory");
;         __syncthreads();
;     }
.LBB0_766:
	s_and_b32 s8, s1, 0x8000
	s_xor_b32 s9, s8, 0x8000
	v_add_u32_e32 v184, s9, v149
	v_add_u32_e32 v185, 0x4000, v184
	v_readfirstlane_b32 s9, v184
	v_lshl_add_u64 v[164:165], v[106:107], 0, s[6:7]
	v_add_u32_e32 v186, 0x1000, v184
	v_readfirstlane_b32 s10, v185
	s_mov_b32 m0, s9
	v_lshl_add_u64 v[170:171], v[120:121], 0, s[6:7]
	v_add_u32_e32 v187, 0x5000, v184
	v_readfirstlane_b32 s11, v186
	global_load_lds_dwordx4 v[164:165], off
	s_mov_b32 m0, s10
	v_lshl_add_u64 v[172:173], v[108:109], 0, s[6:7]
	v_add_u32_e32 v188, 0x2000, v184
	v_readfirstlane_b32 s12, v187
	global_load_lds_dwordx4 v[170:171], off
	s_mov_b32 m0, s11
	v_lshl_add_u64 v[174:175], v[122:123], 0, s[6:7]
	v_add_u32_e32 v189, 0x6000, v184
	v_readfirstlane_b32 s13, v188
	global_load_lds_dwordx4 v[172:173], off
	s_mov_b32 m0, s12
	v_lshl_add_u64 v[176:177], v[110:111], 0, s[6:7]
	v_add_u32_e32 v191, 0x3000, v184
	v_readfirstlane_b32 s16, v189
	global_load_lds_dwordx4 v[174:175], off
	s_mov_b32 m0, s13
	v_lshl_add_u64 v[178:179], v[124:125], 0, s[6:7]
	v_add_u32_e32 v184, 0x7000, v184
	v_readfirstlane_b32 s17, v191
	global_load_lds_dwordx4 v[176:177], off
	s_mov_b32 m0, s16
	v_lshl_add_u64 v[180:181], v[118:119], 0, s[6:7]
	v_readfirstlane_b32 s18, v184
	global_load_lds_dwordx4 v[178:179], off
	s_mov_b32 m0, s17
	v_lshl_add_u64 v[182:183], v[126:127], 0, s[6:7]
	global_load_lds_dwordx4 v[180:181], off
	s_mov_b32 m0, s18
	v_or_b32_e32 v190, s8, v131
	global_load_lds_dwordx4 v[182:183], off
	v_add_u32_e32 v166, s8, v128
	ds_read_b128 v[170:173], v190 offset:16384
	ds_read_b128 v[174:177], v190 offset:16896
	ds_read_b128 v[178:181], v166
	ds_read_b128 v[182:185], v166 offset:2048
	ds_read_b128 v[186:189], v190 offset:20480
	ds_read_b128 v[190:193], v190 offset:20992
	s_waitcnt lgkmcnt(0)
	v_mfma_f32_16x16x32_bf16 v[0:3], v[170:173], v[178:181], v[0:3]
	v_add_u32_e32 v164, s8, v129
	v_or_b32_e32 v165, s8, v130
	s_add_i32 s1, s1, 0x8000
	v_mfma_f32_16x16x32_bf16 v[4:7], v[174:177], v[178:181], v[4:7]
	s_add_u32 s6, s6, 0x80
	s_addc_u32 s7, s7, 0
	s_cmpk_eq_i32 s6, 0x780
	v_mfma_f32_16x16x32_bf16 v[8:11], v[186:189], v[178:181], v[8:11]
	v_mfma_f32_16x16x32_bf16 v[12:15], v[190:193], v[178:181], v[12:15]
	v_mfma_f32_16x16x32_bf16 v[16:19], v[170:173], v[182:185], v[16:19]
	v_mfma_f32_16x16x32_bf16 v[20:23], v[174:177], v[182:185], v[20:23]
	v_mfma_f32_16x16x32_bf16 v[24:27], v[186:189], v[182:185], v[24:27]
	v_mfma_f32_16x16x32_bf16 v[28:31], v[190:193], v[182:185], v[28:31]
	ds_read_b128 v[178:181], v166 offset:4096
	ds_read_b128 v[182:185], v166 offset:6144
	s_waitcnt lgkmcnt(1)
	v_mfma_f32_16x16x32_bf16 v[32:35], v[170:173], v[178:181], v[32:35]
	v_mfma_f32_16x16x32_bf16 v[36:39], v[174:177], v[178:181], v[36:39]
	v_mfma_f32_16x16x32_bf16 v[40:43], v[186:189], v[178:181], v[40:43]
	v_mfma_f32_16x16x32_bf16 v[44:47], v[190:193], v[178:181], v[44:47]
	s_waitcnt lgkmcnt(0)
	v_mfma_f32_16x16x32_bf16 v[48:51], v[170:173], v[182:185], v[48:51]
	v_mfma_f32_16x16x32_bf16 v[52:55], v[174:177], v[182:185], v[52:55]
	ds_read_b128 v[170:173], v165 offset:16384
	ds_read_b128 v[174:177], v165 offset:16896
	v_mfma_f32_16x16x32_bf16 v[56:59], v[186:189], v[182:185], v[56:59]
	v_mfma_f32_16x16x32_bf16 v[60:63], v[190:193], v[182:185], v[60:63]
	ds_read_b128 v[178:181], v164
	ds_read_b128 v[182:185], v164 offset:2048
	ds_read_b128 v[186:189], v165 offset:20480
	ds_read_b128 v[190:193], v165 offset:20992
	s_waitcnt lgkmcnt(3)
	v_mfma_f32_16x16x32_bf16 v[0:3], v[170:173], v[178:181], v[0:3]
	v_mfma_f32_16x16x32_bf16 v[4:7], v[174:177], v[178:181], v[4:7]
	s_waitcnt lgkmcnt(1)
	v_mfma_f32_16x16x32_bf16 v[8:11], v[186:189], v[178:181], v[8:11]
	s_waitcnt lgkmcnt(0)
	v_mfma_f32_16x16x32_bf16 v[12:15], v[190:193], v[178:181], v[12:15]
	v_mfma_f32_16x16x32_bf16 v[16:19], v[170:173], v[182:185], v[16:19]
	v_mfma_f32_16x16x32_bf16 v[20:23], v[174:177], v[182:185], v[20:23]
	v_mfma_f32_16x16x32_bf16 v[24:27], v[186:189], v[182:185], v[24:27]
	v_mfma_f32_16x16x32_bf16 v[28:31], v[190:193], v[182:185], v[28:31]
	ds_read_b128 v[178:181], v164 offset:4096
	ds_read_b128 v[182:185], v164 offset:6144
	s_waitcnt vmcnt(0)
	s_waitcnt lgkmcnt(0)
	v_mfma_f32_16x16x32_bf16 v[32:35], v[170:173], v[178:181], v[32:35]
	s_barrier
	v_mfma_f32_16x16x32_bf16 v[36:39], v[174:177], v[178:181], v[36:39]
	v_mfma_f32_16x16x32_bf16 v[40:43], v[186:189], v[178:181], v[40:43]
	v_mfma_f32_16x16x32_bf16 v[44:47], v[190:193], v[178:181], v[44:47]
	v_mfma_f32_16x16x32_bf16 v[48:51], v[170:173], v[182:185], v[48:51]
	v_mfma_f32_16x16x32_bf16 v[52:55], v[174:177], v[182:185], v[52:55]
	v_mfma_f32_16x16x32_bf16 v[56:59], v[186:189], v[182:185], v[56:59]
	v_mfma_f32_16x16x32_bf16 v[60:63], v[190:193], v[182:185], v[60:63]
	s_cbranch_scc0 .LBB0_766
; __device__ __forceinline__ f32x4 mfma16(bf16x8 a, bf16x8 b, f32x4 c) { return __builtin_amdgcn_mfma_f32_16x16x32_bf16(a, b, c, 0, 0, 0); }
; template <class Epi>
; __device__ __forceinline__ void gemm_tile(const bf16_t* __restrict__ A, const bf16_t* __restrict__ Bt, int K, int row0, int col0, const Epi& epi, char* smem,
;                                           bool prefetched, bool nvalid, int nrow0, int ncol0) {
;     ...
;         const char* cb = smem + cur * 2 * TILE_B;
; #pragma unroll
;         for (int ks = 0; ks < 2; ++ks) {
;             bf16x8 a[4], b[4];
; #pragma unroll
;             for (int m = 0; m < 4; ++m) a[m] = *(const bf16x8*)(cb + offA[m][ks]);
; #pragma unroll
;             for (int n = 0; n < 4; ++n) b[n] = *(const bf16x8*)(cb + offB[n][ks]);
; #pragma unroll
;             for (int m = 0; m < 4; ++m)
; #pragma unroll
;                 for (int n = 0; n < 4; ++n) acc[m][n] = mfma16(b[n], a[m], acc[m][n]);
;         }
;         asm volatile("s_waitcnt vmcnt(0)" ::: "memory");
;         __syncthreads();
;     }
;     if (nvalid) { const bf16_t* qA = A + (size_t)nrow0 * K; const bf16_t* qB = Bt + (size_t)ncol0 * K; GLDS_STAGE(0, qA, qB, 0); }
; template <class E1, class E2>
; __device__ __forceinline__ void gemm_phase2(const bf16_t* A1, const bf16_t* B1, int M1, int N1, const E1& e1,
;                                             const bf16_t* A2, const bf16_t* B2, int M2, int N2, const E2& e2, int K, char* smem) {
;     ...
;     for (int i = (blockIdx.x + (G >> 1)) % G; i < nt2; i += G) {
;         const int j = i + G; const bool nv = j < nt2;
;         gemm_tile(A2, B2, K, (i % nM2) << 7, (i / nM2) << 7, e2, smem, pre, nv, (j % nM2) << 7, (j / nM2) << 7);
	ds_read_b128 v[106:109], v131 offset:49152
	ds_read_b128 v[118:121], v128 offset:32768
	ds_read_b128 v[122:125], v131 offset:49664
	ds_read_b128 v[170:173], v131 offset:53248
	ds_read_b128 v[174:177], v131 offset:53760
	v_readlane_b32 s1, v245, 59
	s_waitcnt lgkmcnt(3)
	v_mfma_f32_16x16x32_bf16 v[0:3], v[106:109], v[118:121], v[0:3]
	s_add_i32 s1, s1, s58
	s_cmpk_gt_i32 s1, 0x7ff
	s_cselect_b64 s[6:7], -1, 0
	s_waitcnt lgkmcnt(2)
	v_mfma_f32_16x16x32_bf16 v[4:7], v[122:125], v[118:121], v[4:7]
	ds_read_b128 v[190:193], v130 offset:49152
	s_cmpk_lt_i32 s1, 0x800
	v_writelane_b32 v245, s1, 59
	s_waitcnt lgkmcnt(2)
	v_mfma_f32_16x16x32_bf16 v[8:11], v[170:173], v[118:121], v[8:11]
	ds_read_b128 v[194:197], v130 offset:53248
	ds_read_b128 v[198:201], v130 offset:53760
	s_waitcnt lgkmcnt(3)
	v_mfma_f32_16x16x32_bf16 v[12:15], v[174:177], v[118:121], v[12:15]
	ds_read_b128 v[118:121], v128 offset:34816
	s_waitcnt lgkmcnt(0)
	v_mfma_f32_16x16x32_bf16 v[16:19], v[106:109], v[118:121], v[16:19]
	v_mfma_f32_16x16x32_bf16 v[20:23], v[122:125], v[118:121], v[20:23]
	v_mfma_f32_16x16x32_bf16 v[24:27], v[170:173], v[118:121], v[24:27]
	v_mfma_f32_16x16x32_bf16 v[28:31], v[174:177], v[118:121], v[28:31]
	ds_read_b128 v[118:121], v128 offset:36864
	s_waitcnt lgkmcnt(0)
	v_mfma_f32_16x16x32_bf16 v[178:181], v[106:109], v[118:121], v[32:35]
	s_nop 2
	ds_read_b128 v[32:35], v128 offset:38912
	v_mfma_f32_16x16x32_bf16 v[182:185], v[122:125], v[118:121], v[36:39]
	v_mfma_f32_16x16x32_bf16 v[186:189], v[170:173], v[118:121], v[40:43]
	v_mfma_f32_16x16x32_bf16 v[118:121], v[174:177], v[118:121], v[44:47]
	s_waitcnt lgkmcnt(0)
	v_mfma_f32_16x16x32_bf16 v[106:109], v[106:109], v[32:35], v[48:51]
	v_mfma_f32_16x16x32_bf16 v[122:125], v[122:125], v[32:35], v[52:55]
	v_mfma_f32_16x16x32_bf16 v[170:173], v[170:173], v[32:35], v[56:59]
	v_mfma_f32_16x16x32_bf16 v[174:177], v[174:177], v[32:35], v[60:63]
	ds_read_b128 v[32:35], v129 offset:32768
	s_waitcnt lgkmcnt(0)
	v_mfma_f32_16x16x32_bf16 v[56:59], v[190:193], v[32:35], v[0:3]
	s_nop 2
	ds_read_b128 v[0:3], v130 offset:49664
	s_waitcnt lgkmcnt(0)
	v_mfma_f32_16x16x32_bf16 v[60:63], v[0:3], v[32:35], v[4:7]
	s_nop 2
	ds_read_b128 v[4:7], v129 offset:34816
	v_mfma_f32_16x16x32_bf16 v[48:51], v[194:197], v[32:35], v[8:11]
	v_mfma_f32_16x16x32_bf16 v[52:55], v[198:201], v[32:35], v[12:15]
	s_nop 2
	ds_read_b128 v[12:15], v129 offset:38912
	s_waitcnt lgkmcnt(1)
	v_mfma_f32_16x16x32_bf16 v[44:47], v[190:193], v[4:7], v[16:19]
	v_mfma_f32_16x16x32_bf16 v[40:43], v[0:3], v[4:7], v[20:23]
	v_mfma_f32_16x16x32_bf16 v[36:39], v[194:197], v[4:7], v[24:27]
	v_mfma_f32_16x16x32_bf16 v[32:35], v[198:201], v[4:7], v[28:31]
	ds_read_b128 v[4:7], v129 offset:36864
	s_waitcnt vmcnt(0)
	s_waitcnt lgkmcnt(0)
	v_mfma_f32_16x16x32_bf16 v[28:31], v[190:193], v[4:7], v[178:181]
	s_barrier
	v_mfma_f32_16x16x32_bf16 v[24:27], v[0:3], v[4:7], v[182:185]
	v_mfma_f32_16x16x32_bf16 v[20:23], v[194:197], v[4:7], v[186:189]
	v_mfma_f32_16x16x32_bf16 v[16:19], v[198:201], v[4:7], v[118:121]
	v_mfma_f32_16x16x32_bf16 v[4:7], v[190:193], v[12:15], v[106:109]
	v_mfma_f32_16x16x32_bf16 v[8:11], v[0:3], v[12:15], v[122:125]
	v_mfma_f32_16x16x32_bf16 v[0:3], v[194:197], v[12:15], v[170:173]
	v_mfma_f32_16x16x32_bf16 v[12:15], v[198:201], v[12:15], v[174:177]
	s_cbranch_scc0 .LBB0_760
	v_readlane_b32 s9, v245, 59
	s_ashr_i32 s1, s9, 31
	s_lshr_b32 s1, s1, 29
	s_add_i32 s1, s9, s1
	s_and_b32 s8, s1, 0x1fffff8
	s_sub_i32 s8, s9, s8
	s_lshl_b32 s8, s8, 7
	s_lshl_b32 s1, s1, 4
	s_ashr_i32 s9, s8, 31
	s_and_b32 s10, s1, 0xffffff80
	s_lshl_b64 s[8:9], s[8:9], 11
	s_add_u32 s8, s14, s8
	s_addc_u32 s9, s15, s9
	s_ashr_i32 s11, s10, 31
	s_lshl_b64 s[10:11], s[10:11], 11
	v_readlane_b32 s1, v245, 53
	s_add_u32 s10, s1, s10
	v_readlane_b32 s1, v245, 54
	s_addc_u32 s11, s1, s11
	v_readfirstlane_b32 s1, v149
	s_mov_b32 m0, s1
	v_readfirstlane_b32 s1, v132
	global_load_lds_dwordx4 v144, s[8:9]
	v_lshl_add_u64 v[106:107], v[64:65], 1, s[10:11]
	s_mov_b32 m0, s1
	v_readfirstlane_b32 s1, v133
	global_load_lds_dwordx4 v[106:107], off
	s_mov_b32 m0, s1
	v_readfirstlane_b32 s1, v134
	global_load_lds_dwordx4 v145, s[8:9]
	v_lshl_add_u64 v[106:107], v[66:67], 1, s[10:11]
	s_mov_b32 m0, s1
	v_readfirstlane_b32 s1, v135
	global_load_lds_dwordx4 v[106:107], off
	s_mov_b32 m0, s1
	v_readfirstlane_b32 s1, v136
	global_load_lds_dwordx4 v162, s[8:9]
	v_lshl_add_u64 v[106:107], v[68:69], 1, s[10:11]
	s_mov_b32 m0, s1
	v_readfirstlane_b32 s1, v137
	global_load_lds_dwordx4 v[106:107], off
	s_mov_b32 m0, s1
	v_readfirstlane_b32 s1, v141
	global_load_lds_dwordx4 v163, s[8:9]
	v_lshl_add_u64 v[106:107], v[70:71], 1, s[10:11]
	s_mov_b32 m0, s1
	s_nop 0
	global_load_lds_dwordx4 v[106:107], off
	s_branch .LBB0_760

; __device__ __forceinline__ f32x4 mfma16(bf16x8 a, bf16x8 b, f32x4 c) { return __builtin_amdgcn_mfma_f32_16x16x32_bf16(a, b, c, 0, 0, 0); }
; template <class Epi>
; __device__ __forceinline__ void gemm_tile(const bf16_t* __restrict__ A, const bf16_t* __restrict__ Bt, int K, int row0, int col0, const Epi& epi, char* smem,
;                                           bool prefetched, bool nvalid, int nrow0, int ncol0) {
;     ...
;     for (int kt = 0; kt < nk; ++kt) {
;         const int cur = kt & 1;
;         if (kt + 1 < nk) GLDS_STAGE(cur ^ 1, pA, pB, kt + 1);
;         const char* cb = smem + cur * 2 * TILE_B;
; #pragma unroll
;         for (int ks = 0; ks < 2; ++ks) {
;             bf16x8 a[4], b[4];
; #pragma unroll
;             for (int m = 0; m < 4; ++m) a[m] = *(const bf16x8*)(cb + offA[m][ks]);
; #pragma unroll
;             for (int n = 0; n < 4; ++n) b[n] = *(const bf16x8*)(cb + offB[n][ks]);
; #pragma unroll
;             for (int m = 0; m < 4; ++m)
; #pragma unroll
;                 for (int n = 0; n < 4; ++n) acc[m][n] = mfma16(b[n], a[m], acc[m][n]);
;         }
;         asm volatile("s_waitcnt vmcnt(0)" ::: "memory");
;         __syncthreads();
;     }
.LBB0_895:
	s_and_b32 s3, s1, 0x8000
	s_xor_b32 s8, s3, 0x8000
	v_add_u32_e32 v172, s8, v149
	v_add_u32_e32 v173, 0x4000, v172
	v_readfirstlane_b32 s8, v172
	v_lshl_add_u64 v[132:133], v[92:93], 0, s[6:7]
	v_add_u32_e32 v174, 0x1000, v172
	v_readfirstlane_b32 s9, v173
	s_mov_b32 m0, s8
	v_lshl_add_u64 v[134:135], v[100:101], 0, s[6:7]
	v_add_u32_e32 v175, 0x5000, v172
	v_readfirstlane_b32 s10, v174
	global_load_lds_dwordx4 v[132:133], off
	s_mov_b32 m0, s9
	v_lshl_add_u64 v[136:137], v[94:95], 0, s[6:7]
	v_add_u32_e32 v176, 0x2000, v172
	v_readfirstlane_b32 s11, v175
	global_load_lds_dwordx4 v[134:135], off
	s_mov_b32 m0, s10
	v_lshl_add_u64 v[138:139], v[102:103], 0, s[6:7]
	v_add_u32_e32 v177, 0x6000, v172
	v_readfirstlane_b32 s12, v176
	global_load_lds_dwordx4 v[136:137], off
	s_mov_b32 m0, s11
	v_lshl_add_u64 v[140:141], v[96:97], 0, s[6:7]
	v_add_u32_e32 v179, 0x3000, v172
	v_readfirstlane_b32 s13, v177
	global_load_lds_dwordx4 v[138:139], off
	s_mov_b32 m0, s12
	v_lshl_add_u64 v[142:143], v[104:105], 0, s[6:7]
	v_add_u32_e32 v172, 0x7000, v172
	v_readfirstlane_b32 s17, v179
	global_load_lds_dwordx4 v[140:141], off
	s_mov_b32 m0, s13
	v_lshl_add_u64 v[144:145], v[98:99], 0, s[6:7]
	v_readfirstlane_b32 s18, v172
	global_load_lds_dwordx4 v[142:143], off
	s_mov_b32 m0, s17
	v_lshl_add_u64 v[170:171], v[106:107], 0, s[6:7]
	global_load_lds_dwordx4 v[144:145], off
	s_mov_b32 m0, s18
	v_or_b32_e32 v178, s3, v110
	global_load_lds_dwordx4 v[170:171], off
	v_add_u32_e32 v131, s3, v108
	ds_read_b128 v[132:135], v178 offset:16384
	ds_read_b128 v[136:139], v178 offset:16896
	ds_read_b128 v[140:143], v131
	ds_read_b128 v[170:173], v131 offset:2048
	ds_read_b128 v[174:177], v178 offset:20480
	ds_read_b128 v[178:181], v178 offset:20992
	s_waitcnt lgkmcnt(0)
	v_mfma_f32_16x16x32_bf16 v[0:3], v[132:135], v[140:143], v[0:3]
	v_or_b32_e32 v144, s3, v111
	s_add_u32 s6, s6, 0x80
	s_addc_u32 s7, s7, 0
	v_mfma_f32_16x16x32_bf16 v[4:7], v[136:139], v[140:143], v[4:7]
	s_add_i32 s1, s1, 0x8000
	s_cmpk_eq_i32 s6, 0x780
	v_mfma_f32_16x16x32_bf16 v[8:11], v[174:177], v[140:143], v[8:11]
	v_mfma_f32_16x16x32_bf16 v[12:15], v[178:181], v[140:143], v[12:15]
	v_mfma_f32_16x16x32_bf16 v[16:19], v[132:135], v[170:173], v[16:19]
	v_mfma_f32_16x16x32_bf16 v[20:23], v[136:139], v[170:173], v[20:23]
	v_mfma_f32_16x16x32_bf16 v[24:27], v[174:177], v[170:173], v[24:27]
	v_mfma_f32_16x16x32_bf16 v[28:31], v[178:181], v[170:173], v[28:31]
	ds_read_b128 v[140:143], v131 offset:4096
	ds_read_b128 v[170:173], v131 offset:6144
	v_add_u32_e32 v131, s3, v109
	s_waitcnt lgkmcnt(1)
	v_mfma_f32_16x16x32_bf16 v[32:35], v[132:135], v[140:143], v[32:35]
	v_mfma_f32_16x16x32_bf16 v[36:39], v[136:139], v[140:143], v[36:39]
	v_mfma_f32_16x16x32_bf16 v[40:43], v[174:177], v[140:143], v[40:43]
	v_mfma_f32_16x16x32_bf16 v[44:47], v[178:181], v[140:143], v[44:47]
	s_waitcnt lgkmcnt(0)
	v_mfma_f32_16x16x32_bf16 v[48:51], v[132:135], v[170:173], v[48:51]
	v_mfma_f32_16x16x32_bf16 v[52:55], v[136:139], v[170:173], v[52:55]
	ds_read_b128 v[132:135], v144 offset:16384
	ds_read_b128 v[136:139], v144 offset:16896
	v_mfma_f32_16x16x32_bf16 v[56:59], v[174:177], v[170:173], v[56:59]
	v_mfma_f32_16x16x32_bf16 v[60:63], v[178:181], v[170:173], v[60:63]
	ds_read_b128 v[140:143], v131
	ds_read_b128 v[170:173], v131 offset:2048
	ds_read_b128 v[174:177], v144 offset:20480
	ds_read_b128 v[178:181], v144 offset:20992
	s_waitcnt lgkmcnt(3)
	v_mfma_f32_16x16x32_bf16 v[0:3], v[132:135], v[140:143], v[0:3]
	v_mfma_f32_16x16x32_bf16 v[4:7], v[136:139], v[140:143], v[4:7]
	s_waitcnt lgkmcnt(1)
	v_mfma_f32_16x16x32_bf16 v[8:11], v[174:177], v[140:143], v[8:11]
	s_waitcnt lgkmcnt(0)
	v_mfma_f32_16x16x32_bf16 v[12:15], v[178:181], v[140:143], v[12:15]
	v_mfma_f32_16x16x32_bf16 v[16:19], v[132:135], v[170:173], v[16:19]
	v_mfma_f32_16x16x32_bf16 v[20:23], v[136:139], v[170:173], v[20:23]
	v_mfma_f32_16x16x32_bf16 v[24:27], v[174:177], v[170:173], v[24:27]
	v_mfma_f32_16x16x32_bf16 v[28:31], v[178:181], v[170:173], v[28:31]
	ds_read_b128 v[140:143], v131 offset:4096
	ds_read_b128 v[170:173], v131 offset:6144
	s_waitcnt vmcnt(0)
	s_waitcnt lgkmcnt(0)
	v_mfma_f32_16x16x32_bf16 v[32:35], v[132:135], v[140:143], v[32:35]
	s_barrier
	v_mfma_f32_16x16x32_bf16 v[36:39], v[136:139], v[140:143], v[36:39]
	v_mfma_f32_16x16x32_bf16 v[40:43], v[174:177], v[140:143], v[40:43]
	v_mfma_f32_16x16x32_bf16 v[44:47], v[178:181], v[140:143], v[44:47]
	v_mfma_f32_16x16x32_bf16 v[48:51], v[132:135], v[170:173], v[48:51]
	v_mfma_f32_16x16x32_bf16 v[52:55], v[136:139], v[170:173], v[52:55]
	v_mfma_f32_16x16x32_bf16 v[56:59], v[174:177], v[170:173], v[56:59]
	v_mfma_f32_16x16x32_bf16 v[60:63], v[178:181], v[170:173], v[60:63]
	s_cbranch_scc0 .LBB0_895
; __device__ __forceinline__ f32x4 mfma16(bf16x8 a, bf16x8 b, f32x4 c) { return __builtin_amdgcn_mfma_f32_16x16x32_bf16(a, b, c, 0, 0, 0); }
; template <class Epi>
; __device__ __forceinline__ void gemm_tile(const bf16_t* __restrict__ A, const bf16_t* __restrict__ Bt, int K, int row0, int col0, const Epi& epi, char* smem,
;                                           bool prefetched, bool nvalid, int nrow0, int ncol0) {
;     ...
;         const char* cb = smem + cur * 2 * TILE_B;
; #pragma unroll
;         for (int ks = 0; ks < 2; ++ks) {
;             bf16x8 a[4], b[4];
; #pragma unroll
;             for (int m = 0; m < 4; ++m) a[m] = *(const bf16x8*)(cb + offA[m][ks]);
; #pragma unroll
;             for (int n = 0; n < 4; ++n) b[n] = *(const bf16x8*)(cb + offB[n][ks]);
; #pragma unroll
;             for (int m = 0; m < 4; ++m)
; #pragma unroll
;                 for (int n = 0; n < 4; ++n) acc[m][n] = mfma16(b[n], a[m], acc[m][n]);
;         }
;         asm volatile("s_waitcnt vmcnt(0)" ::: "memory");
;         __syncthreads();
;     }
;     if (nvalid) { const bf16_t* qA = A + (size_t)nrow0 * K; const bf16_t* qB = Bt + (size_t)ncol0 * K; GLDS_STAGE(0, qA, qB, 0); }
; template <class Epi>
; __device__ __forceinline__ void gemm_phase(const bf16_t* A, const bf16_t* Bt, int M, int N, int K, const Epi& epi, char* smem) {
;     ...
;     for (int i = blockIdx.x; i < ntiles; i += G) {
;         const int j = i + G; const bool nv = j < ntiles;
;         gemm_tile(A, Bt, K, (i / nN) << 7, (i % nN) << 7, epi, smem, pre, nv, (j / nN) << 7, (j % nN) << 7);
	ds_read_b128 v[92:95], v110 offset:49152
	ds_read_b128 v[96:99], v110 offset:49664
	ds_read_b128 v[100:103], v108 offset:32768
	ds_read_b128 v[104:107], v108 offset:34816
	ds_read_b128 v[132:135], v110 offset:53248
	ds_read_b128 v[136:139], v110 offset:53760
	s_add_i32 s16, s16, s58
	s_waitcnt lgkmcnt(3)
	v_mfma_f32_16x16x32_bf16 v[0:3], v[92:95], v[100:103], v[0:3]
	s_cmpk_gt_i32 s16, 0x7ff
	s_cselect_b64 s[6:7], -1, 0
	s_cmpk_lt_i32 s16, 0x800
	v_mfma_f32_16x16x32_bf16 v[4:7], v[96:99], v[100:103], v[4:7]
	s_waitcnt lgkmcnt(1)
	v_mfma_f32_16x16x32_bf16 v[8:11], v[132:135], v[100:103], v[8:11]
	s_waitcnt lgkmcnt(0)
	v_mfma_f32_16x16x32_bf16 v[12:15], v[136:139], v[100:103], v[12:15]
	v_mfma_f32_16x16x32_bf16 v[16:19], v[92:95], v[104:107], v[16:19]
	v_mfma_f32_16x16x32_bf16 v[20:23], v[96:99], v[104:107], v[20:23]
	v_mfma_f32_16x16x32_bf16 v[24:27], v[132:135], v[104:107], v[24:27]
	v_mfma_f32_16x16x32_bf16 v[28:31], v[136:139], v[104:107], v[28:31]
	ds_read_b128 v[100:103], v108 offset:36864
	ds_read_b128 v[104:107], v108 offset:38912
	ds_read_b128 v[178:181], v111 offset:49152
	s_waitcnt lgkmcnt(2)
	v_mfma_f32_16x16x32_bf16 v[140:143], v[92:95], v[100:103], v[32:35]
	v_mfma_f32_16x16x32_bf16 v[170:173], v[96:99], v[100:103], v[36:39]
	v_mfma_f32_16x16x32_bf16 v[174:177], v[132:135], v[100:103], v[40:43]
	v_mfma_f32_16x16x32_bf16 v[100:103], v[136:139], v[100:103], v[44:47]
	s_waitcnt lgkmcnt(1)
	v_mfma_f32_16x16x32_bf16 v[92:95], v[92:95], v[104:107], v[48:51]
	v_mfma_f32_16x16x32_bf16 v[96:99], v[96:99], v[104:107], v[52:55]
	v_mfma_f32_16x16x32_bf16 v[132:135], v[132:135], v[104:107], v[56:59]
	v_mfma_f32_16x16x32_bf16 v[104:107], v[136:139], v[104:107], v[60:63]
	ds_read_b128 v[136:139], v111 offset:49664
	ds_read_b128 v[32:35], v109 offset:32768
	ds_read_b128 v[36:39], v109 offset:34816
	ds_read_b128 v[182:185], v111 offset:53760
	s_waitcnt lgkmcnt(2)
	v_mfma_f32_16x16x32_bf16 v[52:55], v[178:181], v[32:35], v[0:3]
	s_nop 2
	ds_read_b128 v[0:3], v111 offset:53248
	v_mfma_f32_16x16x32_bf16 v[56:59], v[136:139], v[32:35], v[4:7]
	s_nop 2
	ds_read_b128 v[4:7], v109 offset:36864
	ds_read_b128 v[186:189], v109 offset:38912
	s_waitcnt vmcnt(0)
	s_waitcnt lgkmcnt(0)
	v_mfma_f32_16x16x32_bf16 v[60:63], v[0:3], v[32:35], v[8:11]
	s_barrier
	v_mfma_f32_16x16x32_bf16 v[48:51], v[182:185], v[32:35], v[12:15]
	v_mfma_f32_16x16x32_bf16 v[44:47], v[178:181], v[36:39], v[16:19]
	v_mfma_f32_16x16x32_bf16 v[40:43], v[136:139], v[36:39], v[20:23]
	v_mfma_f32_16x16x32_bf16 v[32:35], v[0:3], v[36:39], v[24:27]
	v_mfma_f32_16x16x32_bf16 v[24:27], v[182:185], v[36:39], v[28:31]
	v_mfma_f32_16x16x32_bf16 v[36:39], v[178:181], v[4:7], v[140:143]
	v_mfma_f32_16x16x32_bf16 v[28:31], v[136:139], v[4:7], v[170:173]
	v_mfma_f32_16x16x32_bf16 v[20:23], v[0:3], v[4:7], v[174:177]
	v_mfma_f32_16x16x32_bf16 v[16:19], v[182:185], v[4:7], v[100:103]
	v_mfma_f32_16x16x32_bf16 v[12:15], v[178:181], v[186:189], v[92:95]
	v_mfma_f32_16x16x32_bf16 v[8:11], v[136:139], v[186:189], v[96:99]
	v_mfma_f32_16x16x32_bf16 v[4:7], v[0:3], v[186:189], v[132:135]
	v_mfma_f32_16x16x32_bf16 v[0:3], v[182:185], v[186:189], v[104:107]
	s_cbranch_scc0 .LBB0_889
	s_ashr_i32 s1, s16, 31
	s_lshr_b32 s1, s1, 29
	s_add_i32 s1, s16, s1
	s_lshl_b32 s3, s1, 4
	s_and_b32 s8, s3, 0xffffff80
	s_and_b32 s1, s1, 0x1fffff8
	s_sub_i32 s1, s16, s1
	s_ashr_i32 s9, s8, 31
	s_lshl_b32 s10, s1, 7
	s_lshl_b64 s[8:9], s[8:9], 11
	v_readlane_b32 s12, v245, 60
	v_readlane_b32 s13, v245, 61
	s_add_u32 s8, s12, s8
	s_addc_u32 s9, s13, s9
	s_ashr_i32 s11, s10, 31
	s_lshl_b64 s[10:11], s[10:11], 11
	s_add_u32 s10, s14, s10
	v_readfirstlane_b32 s1, v149
	s_addc_u32 s11, s15, s11
	s_mov_b32 m0, s1
	v_readfirstlane_b32 s1, v118
	global_load_lds_dwordx4 v125, s[8:9]
	v_lshl_add_u64 v[92:93], v[64:65], 1, s[10:11]
	s_mov_b32 m0, s1
	v_readfirstlane_b32 s1, v119
	global_load_lds_dwordx4 v[92:93], off
	s_mov_b32 m0, s1
	v_readfirstlane_b32 s1, v120
	global_load_lds_dwordx4 v126, s[8:9]
	v_lshl_add_u64 v[92:93], v[66:67], 1, s[10:11]
	s_mov_b32 m0, s1
	v_readfirstlane_b32 s1, v121
	global_load_lds_dwordx4 v[92:93], off
	s_mov_b32 m0, s1
	v_readfirstlane_b32 s1, v122
	global_load_lds_dwordx4 v127, s[8:9]
	v_lshl_add_u64 v[92:93], v[68:69], 1, s[10:11]
	s_mov_b32 m0, s1
	v_readfirstlane_b32 s1, v123
	global_load_lds_dwordx4 v[92:93], off
	s_mov_b32 m0, s1
	v_readfirstlane_b32 s1, v124
	global_load_lds_dwordx4 v130, s[8:9]
	v_lshl_add_u64 v[92:93], v[70:71], 1, s[10:11]
	s_mov_b32 m0, s1
	s_nop 0
	global_load_lds_dwordx4 v[92:93], off
	s_branch .LBB0_889

; __device__ __forceinline__ f32x4 mfma16(bf16x8 a, bf16x8 b, f32x4 c) { return __builtin_amdgcn_mfma_f32_16x16x32_bf16(a, b, c, 0, 0, 0); }
; template <class Epi>
; __device__ __forceinline__ void gemm_tile(const bf16_t* __restrict__ A, const bf16_t* __restrict__ Bt, int K, int row0, int col0, const Epi& epi, char* smem,
;                                           bool prefetched, bool nvalid, int nrow0, int ncol0) {
;     ...
;     for (int kt = 0; kt < nk; ++kt) {
;         const int cur = kt & 1;
;         if (kt + 1 < nk) GLDS_STAGE(cur ^ 1, pA, pB, kt + 1);
;         const char* cb = smem + cur * 2 * TILE_B;
; #pragma unroll
;         for (int ks = 0; ks < 2; ++ks) {
;             bf16x8 a[4], b[4];
; #pragma unroll
;             for (int m = 0; m < 4; ++m) a[m] = *(const bf16x8*)(cb + offA[m][ks]);
; #pragma unroll
;             for (int n = 0; n < 4; ++n) b[n] = *(const bf16x8*)(cb + offB[n][ks]);
; #pragma unroll
;             for (int m = 0; m < 4; ++m)
; #pragma unroll
;                 for (int n = 0; n < 4; ++n) acc[m][n] = mfma16(b[n], a[m], acc[m][n]);
;         }
;         asm volatile("s_waitcnt vmcnt(0)" ::: "memory");
;         __syncthreads();
;     }
.LBB0_998:
	s_and_b32 s9, s8, 0x8000
	s_xor_b32 s10, s9, 0x8000
	v_add_u32_e32 v180, s10, v149
	v_add_u32_e32 v181, 0x4000, v180
	v_readfirstlane_b32 s10, v180
	v_lshl_add_u64 v[158:159], v[106:107], 0, s[6:7]
	v_add_u32_e32 v182, 0x1000, v180
	v_readfirstlane_b32 s11, v181
	s_mov_b32 m0, s10
	v_lshl_add_u64 v[160:161], v[120:121], 0, s[6:7]
	v_add_u32_e32 v183, 0x5000, v180
	v_readfirstlane_b32 s12, v182
	global_load_lds_dwordx4 v[158:159], off
	s_mov_b32 m0, s11
	v_lshl_add_u64 v[168:169], v[108:109], 0, s[6:7]
	v_add_u32_e32 v185, 0x2000, v180
	v_readfirstlane_b32 s13, v183
	global_load_lds_dwordx4 v[160:161], off
	s_mov_b32 m0, s12
	v_lshl_add_u64 v[170:171], v[122:123], 0, s[6:7]
	v_add_u32_e32 v186, 0x6000, v180
	v_readfirstlane_b32 s17, v185
	global_load_lds_dwordx4 v[168:169], off
	s_mov_b32 m0, s13
	v_lshl_add_u64 v[172:173], v[110:111], 0, s[6:7]
	v_add_u32_e32 v187, 0x3000, v180
	v_readfirstlane_b32 s18, v186
	global_load_lds_dwordx4 v[170:171], off
	s_mov_b32 m0, s17
	v_lshl_add_u64 v[174:175], v[124:125], 0, s[6:7]
	v_add_u32_e32 v180, 0x7000, v180
	v_readfirstlane_b32 s19, v187
	global_load_lds_dwordx4 v[172:173], off
	s_mov_b32 m0, s18
	v_lshl_add_u64 v[176:177], v[118:119], 0, s[6:7]
	v_readfirstlane_b32 s20, v180
	global_load_lds_dwordx4 v[174:175], off
	s_mov_b32 m0, s19
	v_lshl_add_u64 v[178:179], v[126:127], 0, s[6:7]
	global_load_lds_dwordx4 v[176:177], off
	s_mov_b32 m0, s20
	v_or_b32_e32 v184, s9, v133
	global_load_lds_dwordx4 v[178:179], off
	v_add_u32_e32 v167, s9, v130
	ds_read_b128 v[158:161], v184 offset:16384
	ds_read_b128 v[168:171], v184 offset:16896
	ds_read_b128 v[172:175], v167
	ds_read_b128 v[176:179], v167 offset:2048
	ds_read_b128 v[180:183], v184 offset:20480
	ds_read_b128 v[184:187], v184 offset:20992
	s_waitcnt lgkmcnt(0)
	v_mfma_f32_16x16x32_bf16 v[0:3], v[158:161], v[172:175], v[0:3]
	v_or_b32_e32 v188, s9, v132
	s_add_i32 s8, s8, 0x8000
	s_add_u32 s6, s6, 0x80
	v_mfma_f32_16x16x32_bf16 v[4:7], v[168:171], v[172:175], v[4:7]
	s_addc_u32 s7, s7, 0
	s_cmpk_eq_i32 s6, 0x780
	v_mfma_f32_16x16x32_bf16 v[8:11], v[180:183], v[172:175], v[8:11]
	v_mfma_f32_16x16x32_bf16 v[12:15], v[184:187], v[172:175], v[12:15]
	v_mfma_f32_16x16x32_bf16 v[16:19], v[158:161], v[176:179], v[16:19]
	v_mfma_f32_16x16x32_bf16 v[20:23], v[168:171], v[176:179], v[20:23]
	v_mfma_f32_16x16x32_bf16 v[24:27], v[180:183], v[176:179], v[24:27]
	v_mfma_f32_16x16x32_bf16 v[28:31], v[184:187], v[176:179], v[28:31]
	ds_read_b128 v[172:175], v167 offset:4096
	ds_read_b128 v[176:179], v167 offset:6144
	v_add_u32_e32 v167, s9, v131
	s_waitcnt lgkmcnt(1)
	v_mfma_f32_16x16x32_bf16 v[32:35], v[158:161], v[172:175], v[32:35]
	v_mfma_f32_16x16x32_bf16 v[36:39], v[168:171], v[172:175], v[36:39]
	v_mfma_f32_16x16x32_bf16 v[40:43], v[180:183], v[172:175], v[40:43]
	v_mfma_f32_16x16x32_bf16 v[44:47], v[184:187], v[172:175], v[44:47]
	s_waitcnt lgkmcnt(0)
	v_mfma_f32_16x16x32_bf16 v[48:51], v[158:161], v[176:179], v[48:51]
	v_mfma_f32_16x16x32_bf16 v[52:55], v[168:171], v[176:179], v[52:55]
	ds_read_b128 v[158:161], v188 offset:16384
	ds_read_b128 v[168:171], v188 offset:16896
	v_mfma_f32_16x16x32_bf16 v[56:59], v[180:183], v[176:179], v[56:59]
	v_mfma_f32_16x16x32_bf16 v[60:63], v[184:187], v[176:179], v[60:63]
	ds_read_b128 v[172:175], v167
	ds_read_b128 v[176:179], v167 offset:2048
	ds_read_b128 v[180:183], v188 offset:20480
	ds_read_b128 v[184:187], v188 offset:20992
	s_waitcnt lgkmcnt(3)
	v_mfma_f32_16x16x32_bf16 v[0:3], v[158:161], v[172:175], v[0:3]
	v_mfma_f32_16x16x32_bf16 v[4:7], v[168:171], v[172:175], v[4:7]
	s_waitcnt lgkmcnt(1)
	v_mfma_f32_16x16x32_bf16 v[8:11], v[180:183], v[172:175], v[8:11]
	s_waitcnt lgkmcnt(0)
	v_mfma_f32_16x16x32_bf16 v[12:15], v[184:187], v[172:175], v[12:15]
	v_mfma_f32_16x16x32_bf16 v[16:19], v[158:161], v[176:179], v[16:19]
	v_mfma_f32_16x16x32_bf16 v[20:23], v[168:171], v[176:179], v[20:23]
	v_mfma_f32_16x16x32_bf16 v[24:27], v[180:183], v[176:179], v[24:27]
	v_mfma_f32_16x16x32_bf16 v[28:31], v[184:187], v[176:179], v[28:31]
	ds_read_b128 v[172:175], v167 offset:4096
	ds_read_b128 v[176:179], v167 offset:6144
	s_waitcnt vmcnt(0)
	s_waitcnt lgkmcnt(0)
	v_mfma_f32_16x16x32_bf16 v[32:35], v[158:161], v[172:175], v[32:35]
	s_barrier
	v_mfma_f32_16x16x32_bf16 v[36:39], v[168:171], v[172:175], v[36:39]
	v_mfma_f32_16x16x32_bf16 v[40:43], v[180:183], v[172:175], v[40:43]
	v_mfma_f32_16x16x32_bf16 v[44:47], v[184:187], v[172:175], v[44:47]
	v_mfma_f32_16x16x32_bf16 v[48:51], v[158:161], v[176:179], v[48:51]
	v_mfma_f32_16x16x32_bf16 v[52:55], v[168:171], v[176:179], v[52:55]
	v_mfma_f32_16x16x32_bf16 v[56:59], v[180:183], v[176:179], v[56:59]
	v_mfma_f32_16x16x32_bf16 v[60:63], v[184:187], v[176:179], v[60:63]
	s_cbranch_scc0 .LBB0_998
; __device__ __forceinline__ f32x4 mfma16(bf16x8 a, bf16x8 b, f32x4 c) { return __builtin_amdgcn_mfma_f32_16x16x32_bf16(a, b, c, 0, 0, 0); }
; template <class Epi>
; __device__ __forceinline__ void gemm_tile(const bf16_t* __restrict__ A, const bf16_t* __restrict__ Bt, int K, int row0, int col0, const Epi& epi, char* smem,
;                                           bool prefetched, bool nvalid, int nrow0, int ncol0) {
;     ...
;         const char* cb = smem + cur * 2 * TILE_B;
; #pragma unroll
;         for (int ks = 0; ks < 2; ++ks) {
;             bf16x8 a[4], b[4];
; #pragma unroll
;             for (int m = 0; m < 4; ++m) a[m] = *(const bf16x8*)(cb + offA[m][ks]);
; #pragma unroll
;             for (int n = 0; n < 4; ++n) b[n] = *(const bf16x8*)(cb + offB[n][ks]);
; #pragma unroll
;             for (int m = 0; m < 4; ++m)
; #pragma unroll
;                 for (int n = 0; n < 4; ++n) acc[m][n] = mfma16(b[n], a[m], acc[m][n]);
;         }
;         asm volatile("s_waitcnt vmcnt(0)" ::: "memory");
;         __syncthreads();
;     }
;     if (nvalid) { const bf16_t* qA = A + (size_t)nrow0 * K; const bf16_t* qB = Bt + (size_t)ncol0 * K; GLDS_STAGE(0, qA, qB, 0); }
; template <class Epi>
; __device__ __forceinline__ void gemm_phase(const bf16_t* A, const bf16_t* Bt, int M, int N, int K, const Epi& epi, char* smem) {
;     ...
;     for (int i = blockIdx.x; i < ntiles; i += G) {
;         const int j = i + G; const bool nv = j < ntiles;
;         gemm_tile(A, Bt, K, (i / nN) << 7, (i % nN) << 7, epi, smem, pre, nv, (j / nN) << 7, (j % nN) << 7);
	ds_read_b128 v[106:109], v133 offset:49152
	ds_read_b128 v[118:121], v130 offset:32768
	ds_read_b128 v[122:125], v133 offset:49664
	ds_read_b128 v[158:161], v133 offset:53248
	ds_read_b128 v[168:171], v133 offset:53760
	s_add_i32 s16, s16, s58
	s_waitcnt lgkmcnt(3)
	v_mfma_f32_16x16x32_bf16 v[0:3], v[106:109], v[118:121], v[0:3]
	s_cmpk_gt_i32 s16, 0x1fff
	s_cselect_b64 s[6:7], -1, 0
	s_cmpk_lt_i32 s16, 0x2000
	s_waitcnt lgkmcnt(2)
	v_mfma_f32_16x16x32_bf16 v[4:7], v[122:125], v[118:121], v[4:7]
	ds_read_b128 v[184:187], v132 offset:49152
	ds_read_b128 v[188:191], v132 offset:53760
	s_waitcnt lgkmcnt(3)
	v_mfma_f32_16x16x32_bf16 v[8:11], v[158:161], v[118:121], v[8:11]
	s_waitcnt lgkmcnt(2)
	v_mfma_f32_16x16x32_bf16 v[12:15], v[168:171], v[118:121], v[12:15]
	ds_read_b128 v[118:121], v130 offset:34816
	s_waitcnt lgkmcnt(0)
	v_mfma_f32_16x16x32_bf16 v[16:19], v[106:109], v[118:121], v[16:19]
	v_mfma_f32_16x16x32_bf16 v[20:23], v[122:125], v[118:121], v[20:23]
	v_mfma_f32_16x16x32_bf16 v[24:27], v[158:161], v[118:121], v[24:27]
	v_mfma_f32_16x16x32_bf16 v[28:31], v[168:171], v[118:121], v[28:31]
	ds_read_b128 v[118:121], v130 offset:36864
	s_waitcnt lgkmcnt(0)
	v_mfma_f32_16x16x32_bf16 v[172:175], v[106:109], v[118:121], v[32:35]
	s_nop 2
	ds_read_b128 v[32:35], v130 offset:38912
	v_mfma_f32_16x16x32_bf16 v[176:179], v[122:125], v[118:121], v[36:39]
	v_mfma_f32_16x16x32_bf16 v[180:183], v[158:161], v[118:121], v[40:43]
	v_mfma_f32_16x16x32_bf16 v[118:121], v[168:171], v[118:121], v[44:47]
	s_waitcnt lgkmcnt(0)
	v_mfma_f32_16x16x32_bf16 v[106:109], v[106:109], v[32:35], v[48:51]
	v_mfma_f32_16x16x32_bf16 v[122:125], v[122:125], v[32:35], v[52:55]
	v_mfma_f32_16x16x32_bf16 v[158:161], v[158:161], v[32:35], v[56:59]
	v_mfma_f32_16x16x32_bf16 v[168:171], v[168:171], v[32:35], v[60:63]
	ds_read_b128 v[32:35], v131 offset:32768
	s_waitcnt lgkmcnt(0)
	v_mfma_f32_16x16x32_bf16 v[56:59], v[184:187], v[32:35], v[0:3]
	s_nop 2
	ds_read_b128 v[0:3], v132 offset:49664
	s_waitcnt lgkmcnt(0)
	v_mfma_f32_16x16x32_bf16 v[60:63], v[0:3], v[32:35], v[4:7]
	s_nop 2
	ds_read_b128 v[4:7], v132 offset:53248
	s_waitcnt lgkmcnt(0)
	v_mfma_f32_16x16x32_bf16 v[48:51], v[4:7], v[32:35], v[8:11]
	s_nop 2
	ds_read_b128 v[8:11], v131 offset:34816
	v_mfma_f32_16x16x32_bf16 v[52:55], v[188:191], v[32:35], v[12:15]
	s_waitcnt lgkmcnt(0)
	v_mfma_f32_16x16x32_bf16 v[44:47], v[184:187], v[8:11], v[16:19]
	v_mfma_f32_16x16x32_bf16 v[40:43], v[0:3], v[8:11], v[20:23]
	v_mfma_f32_16x16x32_bf16 v[36:39], v[4:7], v[8:11], v[24:27]
	v_mfma_f32_16x16x32_bf16 v[32:35], v[188:191], v[8:11], v[28:31]
	ds_read_b128 v[8:11], v131 offset:36864
	s_waitcnt lgkmcnt(0)
	v_mfma_f32_16x16x32_bf16 v[16:19], v[188:191], v[8:11], v[118:121]
	s_nop 2
	ds_read_b128 v[118:121], v131 offset:38912
	s_waitcnt vmcnt(0)
	v_mfma_f32_16x16x32_bf16 v[28:31], v[184:187], v[8:11], v[172:175]
	s_waitcnt lgkmcnt(0)
	s_barrier
	v_mfma_f32_16x16x32_bf16 v[24:27], v[0:3], v[8:11], v[176:179]
	v_mfma_f32_16x16x32_bf16 v[20:23], v[4:7], v[8:11], v[180:183]
	v_mfma_f32_16x16x32_bf16 v[8:11], v[184:187], v[118:121], v[106:109]
	v_mfma_f32_16x16x32_bf16 v[12:15], v[0:3], v[118:121], v[122:125]
	v_mfma_f32_16x16x32_bf16 v[0:3], v[4:7], v[118:121], v[158:161]
	v_mfma_f32_16x16x32_bf16 v[4:7], v[188:191], v[118:121], v[168:171]
	s_cbranch_scc0 .LBB0_992
	s_ashr_i32 s8, s16, 31
	s_lshr_b32 s8, s8, 27
	s_add_i32 s9, s16, s8
	s_lshl_b32 s8, s9, 2
	s_and_b32 s9, s9, 0x1ffffe0
	s_and_b32 s8, s8, 0xffffff80
	s_sub_i32 s9, s16, s9
	s_lshl_b32 s10, s9, 7
	s_ashr_i32 s9, s8, 31
	s_lshl_b64 s[8:9], s[8:9], 11
	v_readlane_b32 s11, v245, 53
	s_add_u32 s8, s11, s8
	v_readlane_b32 s11, v245, 54
	s_addc_u32 s9, s11, s9
	s_ashr_i32 s11, s10, 31
	s_lshl_b64 s[10:11], s[10:11], 11
	s_add_u32 s10, s14, s10
	v_readfirstlane_b32 s12, v149
	s_addc_u32 s11, s15, s11
	s_mov_b32 m0, s12
	v_readfirstlane_b32 s12, v134
	global_load_lds_dwordx4 v143, s[8:9]
	v_lshl_add_u64 v[106:107], v[64:65], 1, s[10:11]
	s_mov_b32 m0, s12
	v_readfirstlane_b32 s12, v135
	global_load_lds_dwordx4 v[106:107], off
	s_mov_b32 m0, s12
	v_readfirstlane_b32 s12, v136
	global_load_lds_dwordx4 v144, s[8:9]
	v_lshl_add_u64 v[106:107], v[66:67], 1, s[10:11]
	s_mov_b32 m0, s12
	v_readfirstlane_b32 s12, v137
	global_load_lds_dwordx4 v[106:107], off
	s_mov_b32 m0, s12
	v_readfirstlane_b32 s12, v138
	global_load_lds_dwordx4 v145, s[8:9]
	v_lshl_add_u64 v[106:107], v[68:69], 1, s[10:11]
	s_mov_b32 m0, s12
	v_readfirstlane_b32 s12, v139
	global_load_lds_dwordx4 v[106:107], off
	s_mov_b32 m0, s12
	v_lshl_add_u64 v[106:107], v[70:71], 1, s[10:11]
	global_load_lds_dwordx4 v157, s[8:9]
	v_readfirstlane_b32 s8, v140
	s_mov_b32 m0, s8
	s_nop 0
	global_load_lds_dwordx4 v[106:107], off
	s_branch .LBB0_992

; __device__ __forceinline__ f32x4 mfma16(bf16x8 a, bf16x8 b, f32x4 c) { return __builtin_amdgcn_mfma_f32_16x16x32_bf16(a, b, c, 0, 0, 0); }
; template <class Epi>
; __device__ __forceinline__ void gemm_tile(const bf16_t* __restrict__ A, const bf16_t* __restrict__ Bt, int K, int row0, int col0, const Epi& epi, char* smem,
;                                           bool prefetched, bool nvalid, int nrow0, int ncol0) {
;     ...
;     for (int kt = 0; kt < nk; ++kt) {
;         const int cur = kt & 1;
;         if (kt + 1 < nk) GLDS_STAGE(cur ^ 1, pA, pB, kt + 1);
;         const char* cb = smem + cur * 2 * TILE_B;
; #pragma unroll
;         for (int ks = 0; ks < 2; ++ks) {
;             bf16x8 a[4], b[4];
; #pragma unroll
;             for (int m = 0; m < 4; ++m) a[m] = *(const bf16x8*)(cb + offA[m][ks]);
; #pragma unroll
;             for (int n = 0; n < 4; ++n) b[n] = *(const bf16x8*)(cb + offB[n][ks]);
; #pragma unroll
;             for (int m = 0; m < 4; ++m)
; #pragma unroll
;                 for (int n = 0; n < 4; ++n) acc[m][n] = mfma16(b[n], a[m], acc[m][n]);
;         }
;         asm volatile("s_waitcnt vmcnt(0)" ::: "memory");
;         __syncthreads();
;     }
.LBB0_1054:
	s_and_b32 s3, s1, 0x8000
	s_xor_b32 s6, s3, 0x8000
	v_add_u32_e32 v145, s6, v149
	v_add_u32_e32 v147, 0x4000, v145
	v_readfirstlane_b32 s6, v145
	v_lshl_add_u64 v[128:129], v[92:93], 0, s[4:5]
	v_add_u32_e32 v150, 0x1000, v145
	v_readfirstlane_b32 s7, v147
	s_mov_b32 m0, s6
	v_lshl_add_u64 v[130:131], v[100:101], 0, s[4:5]
	v_add_u32_e32 v151, 0x5000, v145
	v_readfirstlane_b32 s8, v150
	global_load_lds_dwordx4 v[128:129], off
	s_mov_b32 m0, s7
	v_lshl_add_u64 v[132:133], v[94:95], 0, s[4:5]
	v_add_u32_e32 v152, 0x2000, v145
	v_readfirstlane_b32 s9, v151
	global_load_lds_dwordx4 v[130:131], off
	s_mov_b32 m0, s8
	v_lshl_add_u64 v[134:135], v[102:103], 0, s[4:5]
	v_add_u32_e32 v153, 0x6000, v145
	v_readfirstlane_b32 s10, v152
	global_load_lds_dwordx4 v[132:133], off
	s_mov_b32 m0, s9
	v_lshl_add_u64 v[136:137], v[96:97], 0, s[4:5]
	v_add_u32_e32 v154, 0x3000, v145
	v_readfirstlane_b32 s11, v153
	global_load_lds_dwordx4 v[134:135], off
	s_mov_b32 m0, s10
	v_lshl_add_u64 v[138:139], v[104:105], 0, s[4:5]
	v_add_u32_e32 v145, 0x7000, v145
	v_readfirstlane_b32 s14, v154
	global_load_lds_dwordx4 v[136:137], off
	s_mov_b32 m0, s11
	v_lshl_add_u64 v[140:141], v[98:99], 0, s[4:5]
	v_readfirstlane_b32 s15, v145
	global_load_lds_dwordx4 v[138:139], off
	s_mov_b32 m0, s14
	v_lshl_add_u64 v[142:143], v[106:107], 0, s[4:5]
	global_load_lds_dwordx4 v[140:141], off
	s_mov_b32 m0, s15
	v_or_b32_e32 v144, s3, v110
	global_load_lds_dwordx4 v[142:143], off
	v_add_u32_e32 v127, s3, v108
	ds_read_b128 v[128:131], v144 offset:16384
	ds_read_b128 v[132:135], v144 offset:16896
	ds_read_b128 v[136:139], v127
	ds_read_b128 v[140:143], v127 offset:2048
	ds_read_b128 v[150:153], v144 offset:20480
	ds_read_b128 v[154:157], v144 offset:20992
	s_waitcnt lgkmcnt(0)
	v_mfma_f32_16x16x32_bf16 v[0:3], v[128:131], v[136:139], v[0:3]
	v_or_b32_e32 v144, s3, v111
	s_add_u32 s4, s4, 0x80
	s_addc_u32 s5, s5, 0
	v_mfma_f32_16x16x32_bf16 v[4:7], v[132:135], v[136:139], v[4:7]
	s_add_i32 s1, s1, 0x8000
	s_cmpk_eq_i32 s4, 0x1f80
	v_mfma_f32_16x16x32_bf16 v[8:11], v[150:153], v[136:139], v[8:11]
	v_mfma_f32_16x16x32_bf16 v[12:15], v[154:157], v[136:139], v[12:15]
	v_mfma_f32_16x16x32_bf16 v[16:19], v[128:131], v[140:143], v[16:19]
	v_mfma_f32_16x16x32_bf16 v[20:23], v[132:135], v[140:143], v[20:23]
	v_mfma_f32_16x16x32_bf16 v[24:27], v[150:153], v[140:143], v[24:27]
	v_mfma_f32_16x16x32_bf16 v[28:31], v[154:157], v[140:143], v[28:31]
	ds_read_b128 v[136:139], v127 offset:4096
	ds_read_b128 v[140:143], v127 offset:6144
	v_add_u32_e32 v127, s3, v109
	s_waitcnt lgkmcnt(1)
	v_mfma_f32_16x16x32_bf16 v[32:35], v[128:131], v[136:139], v[32:35]
	v_mfma_f32_16x16x32_bf16 v[36:39], v[132:135], v[136:139], v[36:39]
	v_mfma_f32_16x16x32_bf16 v[40:43], v[150:153], v[136:139], v[40:43]
	v_mfma_f32_16x16x32_bf16 v[44:47], v[154:157], v[136:139], v[44:47]
	s_waitcnt lgkmcnt(0)
	v_mfma_f32_16x16x32_bf16 v[48:51], v[128:131], v[140:143], v[48:51]
	v_mfma_f32_16x16x32_bf16 v[52:55], v[132:135], v[140:143], v[52:55]
	ds_read_b128 v[128:131], v144 offset:16384
	ds_read_b128 v[132:135], v144 offset:16896
	v_mfma_f32_16x16x32_bf16 v[56:59], v[150:153], v[140:143], v[56:59]
	v_mfma_f32_16x16x32_bf16 v[60:63], v[154:157], v[140:143], v[60:63]
	ds_read_b128 v[136:139], v127
	ds_read_b128 v[140:143], v127 offset:2048
	ds_read_b128 v[150:153], v144 offset:20480
	ds_read_b128 v[154:157], v144 offset:20992
	s_waitcnt lgkmcnt(3)
	v_mfma_f32_16x16x32_bf16 v[0:3], v[128:131], v[136:139], v[0:3]
	v_mfma_f32_16x16x32_bf16 v[4:7], v[132:135], v[136:139], v[4:7]
	s_waitcnt lgkmcnt(1)
	v_mfma_f32_16x16x32_bf16 v[8:11], v[150:153], v[136:139], v[8:11]
	s_waitcnt lgkmcnt(0)
	v_mfma_f32_16x16x32_bf16 v[12:15], v[154:157], v[136:139], v[12:15]
	v_mfma_f32_16x16x32_bf16 v[16:19], v[128:131], v[140:143], v[16:19]
	v_mfma_f32_16x16x32_bf16 v[20:23], v[132:135], v[140:143], v[20:23]
	v_mfma_f32_16x16x32_bf16 v[24:27], v[150:153], v[140:143], v[24:27]
	v_mfma_f32_16x16x32_bf16 v[28:31], v[154:157], v[140:143], v[28:31]
	ds_read_b128 v[136:139], v127 offset:4096
	ds_read_b128 v[140:143], v127 offset:6144
	s_waitcnt vmcnt(0)
	s_waitcnt lgkmcnt(0)
	v_mfma_f32_16x16x32_bf16 v[32:35], v[128:131], v[136:139], v[32:35]
	s_barrier
	v_mfma_f32_16x16x32_bf16 v[36:39], v[132:135], v[136:139], v[36:39]
	v_mfma_f32_16x16x32_bf16 v[40:43], v[150:153], v[136:139], v[40:43]
	v_mfma_f32_16x16x32_bf16 v[44:47], v[154:157], v[136:139], v[44:47]
	v_mfma_f32_16x16x32_bf16 v[48:51], v[128:131], v[140:143], v[48:51]
	v_mfma_f32_16x16x32_bf16 v[52:55], v[132:135], v[140:143], v[52:55]
	v_mfma_f32_16x16x32_bf16 v[56:59], v[150:153], v[140:143], v[56:59]
	v_mfma_f32_16x16x32_bf16 v[60:63], v[154:157], v[140:143], v[60:63]
	s_cbranch_scc0 .LBB0_1054
; __device__ __forceinline__ f32x4 mfma16(bf16x8 a, bf16x8 b, f32x4 c) { return __builtin_amdgcn_mfma_f32_16x16x32_bf16(a, b, c, 0, 0, 0); }
; template <class Epi>
; __device__ __forceinline__ void gemm_tile(const bf16_t* __restrict__ A, const bf16_t* __restrict__ Bt, int K, int row0, int col0, const Epi& epi, char* smem,
;                                           bool prefetched, bool nvalid, int nrow0, int ncol0) {
;     ...
;         const char* cb = smem + cur * 2 * TILE_B;
; #pragma unroll
;         for (int ks = 0; ks < 2; ++ks) {
;             bf16x8 a[4], b[4];
; #pragma unroll
;             for (int m = 0; m < 4; ++m) a[m] = *(const bf16x8*)(cb + offA[m][ks]);
; #pragma unroll
;             for (int n = 0; n < 4; ++n) b[n] = *(const bf16x8*)(cb + offB[n][ks]);
; #pragma unroll
;             for (int m = 0; m < 4; ++m)
; #pragma unroll
;                 for (int n = 0; n < 4; ++n) acc[m][n] = mfma16(b[n], a[m], acc[m][n]);
;         }
;         asm volatile("s_waitcnt vmcnt(0)" ::: "memory");
;         __syncthreads();
;     }
;     if (nvalid) { const bf16_t* qA = A + (size_t)nrow0 * K; const bf16_t* qB = Bt + (size_t)ncol0 * K; GLDS_STAGE(0, qA, qB, 0); }
; template <class Epi>
; __device__ __forceinline__ void gemm_phase(const bf16_t* A, const bf16_t* Bt, int M, int N, int K, const Epi& epi, char* smem) {
;     ...
;     for (int i = blockIdx.x; i < ntiles; i += G) {
;         const int j = i + G; const bool nv = j < ntiles;
;         gemm_tile(A, Bt, K, (i / nN) << 7, (i % nN) << 7, epi, smem, pre, nv, (j / nN) << 7, (j % nN) << 7);
	ds_read_b128 v[92:95], v110 offset:49152
	ds_read_b128 v[96:99], v110 offset:49664
	ds_read_b128 v[100:103], v108 offset:32768
	ds_read_b128 v[104:107], v108 offset:34816
	ds_read_b128 v[128:131], v110 offset:53248
	ds_read_b128 v[132:135], v110 offset:53760
	s_add_i32 s16, s16, s58
	s_waitcnt lgkmcnt(3)
	v_mfma_f32_16x16x32_bf16 v[0:3], v[92:95], v[100:103], v[0:3]
	s_cmpk_gt_i32 s16, 0x7ff
	s_cselect_b64 s[4:5], -1, 0
	s_cmpk_lt_i32 s16, 0x800
	v_mfma_f32_16x16x32_bf16 v[4:7], v[96:99], v[100:103], v[4:7]
	s_waitcnt lgkmcnt(1)
	v_mfma_f32_16x16x32_bf16 v[8:11], v[128:131], v[100:103], v[8:11]
	s_waitcnt lgkmcnt(0)
	v_mfma_f32_16x16x32_bf16 v[12:15], v[132:135], v[100:103], v[12:15]
	v_mfma_f32_16x16x32_bf16 v[16:19], v[92:95], v[104:107], v[16:19]
	v_mfma_f32_16x16x32_bf16 v[20:23], v[96:99], v[104:107], v[20:23]
	v_mfma_f32_16x16x32_bf16 v[24:27], v[128:131], v[104:107], v[24:27]
	v_mfma_f32_16x16x32_bf16 v[28:31], v[132:135], v[104:107], v[28:31]
	ds_read_b128 v[100:103], v108 offset:36864
	ds_read_b128 v[104:107], v108 offset:38912
	ds_read_b128 v[154:157], v111 offset:49152
	s_waitcnt lgkmcnt(2)
	v_mfma_f32_16x16x32_bf16 v[136:139], v[92:95], v[100:103], v[32:35]
	v_mfma_f32_16x16x32_bf16 v[140:143], v[96:99], v[100:103], v[36:39]
	v_mfma_f32_16x16x32_bf16 v[150:153], v[128:131], v[100:103], v[40:43]
	v_mfma_f32_16x16x32_bf16 v[100:103], v[132:135], v[100:103], v[44:47]
	s_waitcnt lgkmcnt(1)
	v_mfma_f32_16x16x32_bf16 v[92:95], v[92:95], v[104:107], v[48:51]
	v_mfma_f32_16x16x32_bf16 v[96:99], v[96:99], v[104:107], v[52:55]
	v_mfma_f32_16x16x32_bf16 v[128:131], v[128:131], v[104:107], v[56:59]
	v_mfma_f32_16x16x32_bf16 v[104:107], v[132:135], v[104:107], v[60:63]
	ds_read_b128 v[132:135], v111 offset:49664
	ds_read_b128 v[32:35], v109 offset:32768
	ds_read_b128 v[36:39], v109 offset:34816
	ds_read_b128 v[158:161], v111 offset:53760
	s_waitcnt lgkmcnt(2)
	v_mfma_f32_16x16x32_bf16 v[52:55], v[154:157], v[32:35], v[0:3]
	s_nop 2
	ds_read_b128 v[0:3], v111 offset:53248
	v_mfma_f32_16x16x32_bf16 v[56:59], v[132:135], v[32:35], v[4:7]
	s_nop 2
	ds_read_b128 v[4:7], v109 offset:36864
	ds_read_b128 v[168:171], v109 offset:38912
	s_waitcnt vmcnt(0)
	s_waitcnt lgkmcnt(0)
	v_mfma_f32_16x16x32_bf16 v[60:63], v[0:3], v[32:35], v[8:11]
	s_barrier
	v_mfma_f32_16x16x32_bf16 v[48:51], v[158:161], v[32:35], v[12:15]
	v_mfma_f32_16x16x32_bf16 v[44:47], v[154:157], v[36:39], v[16:19]
	v_mfma_f32_16x16x32_bf16 v[40:43], v[132:135], v[36:39], v[20:23]
	v_mfma_f32_16x16x32_bf16 v[32:35], v[0:3], v[36:39], v[24:27]
	v_mfma_f32_16x16x32_bf16 v[24:27], v[158:161], v[36:39], v[28:31]
	v_mfma_f32_16x16x32_bf16 v[36:39], v[154:157], v[4:7], v[136:139]
	v_mfma_f32_16x16x32_bf16 v[28:31], v[132:135], v[4:7], v[140:143]
	v_mfma_f32_16x16x32_bf16 v[20:23], v[0:3], v[4:7], v[150:153]
	v_mfma_f32_16x16x32_bf16 v[16:19], v[158:161], v[4:7], v[100:103]
	v_mfma_f32_16x16x32_bf16 v[12:15], v[154:157], v[168:171], v[92:95]
	v_mfma_f32_16x16x32_bf16 v[8:11], v[132:135], v[168:171], v[96:99]
	v_mfma_f32_16x16x32_bf16 v[4:7], v[0:3], v[168:171], v[128:131]
	v_mfma_f32_16x16x32_bf16 v[0:3], v[158:161], v[168:171], v[104:107]
	s_cbranch_scc0 .LBB0_1048
	s_ashr_i32 s1, s16, 31
	s_lshr_b32 s1, s1, 29
	s_add_i32 s1, s16, s1
	s_lshl_b32 s3, s1, 4
	s_and_b32 s6, s3, 0xffffff80
	s_and_b32 s1, s1, 0x1fffff8
	s_sub_i32 s1, s16, s1
	s_ashr_i32 s7, s6, 31
	s_lshl_b32 s8, s1, 7
	s_lshl_b64 s[6:7], s[6:7], 13
	v_readlane_b32 s10, v245, 55
	v_readlane_b32 s11, v245, 56
	s_add_u32 s6, s10, s6
	s_addc_u32 s7, s11, s7
	s_ashr_i32 s9, s8, 31
	s_lshl_b64 s[8:9], s[8:9], 13
	s_add_u32 s8, s12, s8
	v_readfirstlane_b32 s1, v149
	s_addc_u32 s9, s13, s9
	s_mov_b32 m0, s1
	v_readfirstlane_b32 s1, v114
	global_load_lds_dwordx4 v123, s[6:7]
	v_lshl_add_u64 v[92:93], v[64:65], 1, s[8:9]
	s_mov_b32 m0, s1
	v_readfirstlane_b32 s1, v116
	global_load_lds_dwordx4 v[92:93], off
	s_mov_b32 m0, s1
	v_readfirstlane_b32 s1, v118
	global_load_lds_dwordx4 v124, s[6:7]
	v_lshl_add_u64 v[92:93], v[66:67], 1, s[8:9]
	s_mov_b32 m0, s1
	v_readfirstlane_b32 s1, v119
	global_load_lds_dwordx4 v[92:93], off
	s_mov_b32 m0, s1
	v_readfirstlane_b32 s1, v120
	global_load_lds_dwordx4 v125, s[6:7]
	v_lshl_add_u64 v[92:93], v[68:69], 1, s[8:9]
	s_mov_b32 m0, s1
	v_readfirstlane_b32 s1, v121
	global_load_lds_dwordx4 v[92:93], off
	s_mov_b32 m0, s1
	v_readfirstlane_b32 s1, v122
	global_load_lds_dwordx4 v126, s[6:7]
	v_lshl_add_u64 v[92:93], v[70:71], 1, s[8:9]
	s_mov_b32 m0, s1
	s_nop 0
	global_load_lds_dwordx4 v[92:93], off
	s_branch .LBB0_1048
